# P3: the 32 pooling tiles beyond two full rounds taken by scan workgroups 0..15 after their scan (on top of both scan changes)
# baseline (speedup 1.0000x reference)
; __global__ void __launch_bounds__(512) hymba_fwd(Params p) {
;     ...
;         } else {
;             const int ob = bid - nsb, no = G - nsb;
;             for (int t0 = 2 * ob; t0 < NSM; t0 += 2 * no) gdn_sample_item(p, min(t0 + vb, NSM - 1), vlds);
;             for (int t0 = 2 * ob; t0 < NPL; t0 += 2 * no) { const int t = min(t0 + vb, NPL - 1); int nt, mt; tile_map(t, 68, 8, mt, nt); const int g = nt >> 1;
.LBB0_868:
	s_movk_i32 s98, 0x220
	s_cmpk_lg_i32 s33, 0x100
	s_cbranch_scc1 .Lpool_in
	s_movk_i32 s98, 0x200

; #define GLDS_STAGE(st, kt_) do { \
;         _Pragma("unroll") for (int i_ = 0; i_ < FI; ++i_) { \
;             glds16(ap + (size_t)(32 * i_) * lda + (kt_) * 64, l3a + (st) + tid * 16 + i_ * 4096); \
;             glds16(bp + (size_t)(32 * i_) * ldb + (kt_) * 64, l3a + (st) + OPB + tid * 16 + i_ * 4096); } } while (0)
; template <int WT, class Epi>
; DEV void gemm_tile(const bf16_t* __restrict__ A, int lda, const bf16_t* __restrict__ Bt, int ldb, int K, unsigned char* lds, const Epi& epi) {
;     ...
;     constexpr int NSTG = 65536 / STB;
; #pragma unroll
;     for (int s_ = 0; s_ < NSTG - 1; ++s_) if (s_ < nk) GLDS_STAGE(s_ * STB, s_);
;     const int aoff = (wr * WT + fr) * 128, boff = OPB + (wc * WT + fr) * 128, sw = fr & 7;
;     int cur = 0, nxt = (NSTG - 1) * STB;
;     for (int kt = 0; kt < nk; ++kt) {
;         if (NSTG == 4 && kt + 2 < nk) { if (FI == 2) asm volatile("s_waitcnt vmcnt(8)" ::: "memory"); else asm volatile("s_waitcnt vmcnt(0)" ::: "memory"); }
;         else asm volatile("s_waitcnt vmcnt(0)" ::: "memory");
;         __syncthreads();
;         if (kt + NSTG - 1 < nk) GLDS_STAGE(nxt, kt + NSTG - 1);
; #pragma unroll
;         for (int kh = 0; kh < 2; ++kh) {
;             bf16x8 af[FI], bfr[FI];
;             const int ch = ((kh * 4 + fq) ^ sw) << 4;
; #pragma unroll
;             for (int i = 0; i < FI; ++i) { af[i] = *(const bf16x8*)(lds + cur + aoff + i * 2048 + ch); bfr[i] = *(const bf16x8*)(lds + cur + boff + i * 2048 + ch); }
; #pragma unroll
;             for (int mi = 0; mi < FI; ++mi)
; #pragma unroll
;                 for (int ni = 0; ni < FI; ++ni) acc[mi][ni] = __builtin_amdgcn_mfma_f32_16x16x32_bf16(bfr[ni], af[mi], acc[mi][ni], 0, 0, 0);
; __global__ void __launch_bounds__(512) hymba_fwd(Params p) {
;     ...
;             for (int t0 = 2 * ob; t0 < NPL; t0 += 2 * no) { const int t = min(t0 + vb, NPL - 1); int nt, mt; tile_map(t, 68, 8, mt, nt); const int g = nt >> 1;
;                 EpiPoolS e{mt * 128, nt * 128, proj, p.in[15], mix + (size_t)mt * 128 * LDB + 1024 + nt * 128, LDB};
;                 gemm_tile<64>(dpl + (size_t)mt * 128 * LDP + g * 256, LDP, Wt_pool + (size_t)nt * 128 * LDM, LDM, 256, vlds, e);
.LBB0_870:
	s_add_i32 s14, s71, s72
	s_min_i32 s14, s14, 0x21f
	s_and_b32 s15, s14, 7
	s_mulk_i32 s15, 0x44
	s_ashr_i32 s14, s14, 3
	s_add_i32 s14, s15, s14
	s_ashr_i32 s15, s14, 31
	s_lshr_b32 s15, s15, 26
	s_add_i32 s15, s14, s15
	s_ashr_i32 s68, s15, 6
	s_lshl_b32 s81, s68, 3
	s_sub_i32 s68, 0x44, s81
	s_andn2_b32 s15, s15, 63
	s_min_u32 s82, s68, 8
	s_sub_i32 s14, s14, s15
	s_sext_i32_i8 s15, s14
	v_cvt_f32_ubyte0_e32 v3, s82
	v_cvt_f32_i32_e32 v2, s15
	v_rcp_iflag_f32_e32 v4, v3
	s_ashr_i32 s68, s15, 30
	s_or_b32 s83, s68, 1
	v_mov_b32_e32 v137, v1
	v_mul_f32_e32 v4, v2, v4
	v_trunc_f32_e32 v4, v4
	v_fma_f32 v2, -v4, v3, v2
	v_cvt_i32_f32_e32 v4, v4
	v_cmp_ge_f32_e64 s[68:69], |v2|, v3
	s_and_b64 s[68:69], s[68:69], exec
	s_cselect_b32 s15, s83, 0
	v_readfirstlane_b32 s68, v4
	s_add_i32 s15, s68, s15
	s_sext_i32_i8 s84, s15
	s_mul_i32 s15, s15, s82
	s_sub_i32 s14, s14, s15
	s_sext_i32_i8 s14, s14
	s_add_i32 s14, s81, s14
	s_lshl_b32 s68, s84, 7
	v_mad_i64_i32 v[2:3], s[82:83], s14, v134, v[174:175]
	s_ashr_i32 s69, s68, 31
	v_lshl_add_u64 v[132:133], s[68:69], 1, v[2:3]
	v_mad_i64_i32 v[2:3], s[82:83], s14, v135, v[140:141]
	s_and_b32 s82, s68, 0xffffff00
	s_ashr_i32 s83, s82, 31
	v_ashrrev_i32_e32 v6, 3, v137
	v_xor_b32_e32 v7, v6, v137
	v_lshl_add_u64 v[2:3], s[82:83], 1, v[2:3]
	v_mad_i64_i32 v[4:5], s[82:83], s84, v136, v[138:139]
	v_lshlrev_b32_e32 v7, 4, v7
	v_lshlrev_b32_e32 v9, 4, v137
	v_mad_i64_i32 v[2:3], s[82:83], v6, s77, v[2:3]
	v_and_b32_e32 v130, 0x70, v7
	v_mad_i64_i32 v[4:5], s[82:83], v6, s78, v[4:5]
	v_add_u32_e32 v6, s70, v9
	s_lshl_b32 s81, s14, 7
	v_lshl_add_u64 v[2:3], v[2:3], 0, v[130:131]
	v_add_u32_e32 v7, 0x4000, v6
	v_readfirstlane_b32 s14, v6
	s_mov_b32 s15, m0
	s_mov_b32 m0, s14
	s_nop 0
	global_load_lds_dwordx4 v[2:3], off
	s_mov_b32 m0, s15
	v_lshl_add_u64 v[4:5], v[4:5], 0, v[130:131]
	v_readfirstlane_b32 s15, v7
	s_mov_b32 s82, m0
	s_mov_b32 m0, s15
	s_nop 0
	global_load_lds_dwordx4 v[4:5], off
	s_mov_b32 m0, s82
	v_lshl_add_u64 v[6:7], v[2:3], 0, s[6:7]
	s_add_i32 s82, s14, 0x1000
	s_mov_b32 s83, m0
	s_mov_b32 m0, s82
	s_nop 0
	global_load_lds_dwordx4 v[6:7], off
	s_mov_b32 m0, s83
	v_lshl_add_u64 v[6:7], v[4:5], 0, s[8:9]
	s_add_i32 s83, s15, 0x1000
	s_mov_b32 s84, m0
	s_mov_b32 m0, s83
	s_nop 0
	global_load_lds_dwordx4 v[6:7], off
	s_mov_b32 m0, s84
	v_lshl_add_u64 v[6:7], v[2:3], 0, s[10:11]
	s_add_i32 s83, s14, 0x2000
	s_mov_b32 s84, m0
	s_mov_b32 m0, s83
	s_nop 0
	global_load_lds_dwordx4 v[6:7], off
	s_mov_b32 m0, s84
	v_lshl_add_u64 v[6:7], v[4:5], 0, s[12:13]
	s_add_i32 s84, s15, 0x2000
	s_mov_b32 s85, m0
	s_mov_b32 m0, s84
	s_nop 0
	global_load_lds_dwordx4 v[6:7], off
	s_mov_b32 m0, s85
	v_lshl_add_u64 v[6:7], v[2:3], 0, s[16:17]
	s_add_i32 s84, s14, 0x3000
	s_mov_b32 s85, m0
	s_mov_b32 m0, s84
	s_nop 0
	global_load_lds_dwordx4 v[6:7], off
	s_mov_b32 m0, s85
	v_lshl_add_u64 v[6:7], v[4:5], 0, s[18:19]
	v_and_b32_e32 v8, 15, v137
	s_addk_i32 s15, 0x3000
	s_mov_b32 s85, m0
	s_mov_b32 m0, s15
	s_nop 0
	global_load_lds_dwordx4 v[6:7], off
	s_mov_b32 m0, s85
	v_ashrrev_i32_e32 v6, 1, v137
	v_and_or_b32 v130, v6, s76, v8
	v_lshlrev_b32_e32 v6, 7, v137
	v_add_u32_e32 v102, 0x4000, v9
	v_add_u32_e32 v12, s73, v9
	v_and_b32_e32 v11, 0x2780, v6
	s_waitcnt vmcnt(0)
	s_waitcnt lgkmcnt(0)
	s_barrier
	v_lshl_add_u64 v[6:7], v[2:3], 0, s[20:21]
	v_add_u32_e32 v13, s73, v102
	v_readfirstlane_b32 s15, v12
	s_mov_b32 s85, m0
	s_mov_b32 m0, s15
	s_nop 0
	global_load_lds_dwordx4 v[6:7], off
	s_mov_b32 m0, s85
	v_lshl_add_u64 v[8:9], v[4:5], 0, s[20:21]
	v_readfirstlane_b32 s85, v13
	s_mov_b32 s86, m0
	s_mov_b32 m0, s85
	s_nop 0
	global_load_lds_dwordx4 v[8:9], off
	s_mov_b32 m0, s86
	v_lshl_add_u64 v[6:7], v[2:3], 0, s[22:23]
	s_add_i32 s86, s15, 0x1000
	s_mov_b32 s87, m0
	s_mov_b32 m0, s86
	s_nop 0
	global_load_lds_dwordx4 v[6:7], off
	s_mov_b32 m0, s87
	v_lshl_add_u64 v[6:7], v[4:5], 0, s[24:25]
	s_add_i32 s87, s85, 0x1000
	s_mov_b32 s88, m0
	s_mov_b32 m0, s87
	s_nop 0
	global_load_lds_dwordx4 v[6:7], off
	s_mov_b32 m0, s88
	v_lshl_add_u64 v[6:7], v[2:3], 0, s[26:27]
	s_add_i32 s88, s15, 0x2000
	s_mov_b32 s89, m0
	s_mov_b32 m0, s88
	s_nop 0
	global_load_lds_dwordx4 v[6:7], off
	s_mov_b32 m0, s89
	v_lshl_add_u64 v[6:7], v[4:5], 0, s[30:31]
	s_add_i32 s89, s85, 0x2000
	s_mov_b32 s90, m0
	s_mov_b32 m0, s89
	s_nop 0
	global_load_lds_dwordx4 v[6:7], off
	s_mov_b32 m0, s90
	v_lshl_add_u64 v[6:7], v[2:3], 0, s[34:35]
	v_lshrrev_b32_e32 v10, 4, v137
	v_and_b32_e32 v74, 7, v137
	s_add_i32 s90, s15, 0x3000
	s_mov_b32 s91, m0
	s_mov_b32 m0, s90
	s_nop 0
	global_load_lds_dwordx4 v[6:7], off
	s_mov_b32 m0, s91
	v_lshl_add_u64 v[6:7], v[4:5], 0, s[36:37]
	s_add_i32 s91, s85, 0x3000
	s_mov_b32 s92, m0
	s_mov_b32 m0, s91
	s_nop 0
	global_load_lds_dwordx4 v[6:7], off
	s_mov_b32 m0, s92
	v_bitop3_b32 v6, v10, v74, 3 bitop3:0x6c
	v_lshl_add_u32 v75, v130, 7, s70
	v_lshlrev_b32_e32 v6, 4, v6
	v_add_u32_e32 v76, s70, v11
	v_add_u32_e32 v126, v75, v6
	v_add_u32_e32 v118, v76, v6
	ds_read_b128 v[6:9], v126
	ds_read_b128 v[10:13], v118 offset:16384
	ds_read_b128 v[14:17], v126 offset:2048
	ds_read_b128 v[18:21], v118 offset:18432
	ds_read_b128 v[22:25], v126 offset:4096
	ds_read_b128 v[26:29], v118 offset:20480
	ds_read_b128 v[30:33], v126 offset:6144
	ds_read_b128 v[34:37], v118 offset:22528
	v_bfe_u32 v142, v137, 4, 2
	s_waitcnt lgkmcnt(6)
	v_mfma_f32_16x16x32_bf16 v[38:41], v[10:13], v[6:9], 0
	v_and_b32_e32 v143, 64, v137
	s_add_i32 s72, s72, s74
	s_waitcnt lgkmcnt(4)
	v_mfma_f32_16x16x32_bf16 v[42:45], v[18:21], v[6:9], 0
	s_waitcnt lgkmcnt(2)
	v_mfma_f32_16x16x32_bf16 v[46:49], v[26:29], v[6:9], 0
	s_waitcnt lgkmcnt(0)
	v_mfma_f32_16x16x32_bf16 v[6:9], v[34:37], v[6:9], 0
	v_mfma_f32_16x16x32_bf16 v[50:53], v[10:13], v[14:17], 0
	v_mfma_f32_16x16x32_bf16 v[54:57], v[18:21], v[14:17], 0
	v_mfma_f32_16x16x32_bf16 v[58:61], v[26:29], v[14:17], 0
	v_mfma_f32_16x16x32_bf16 v[14:17], v[34:37], v[14:17], 0
	v_mfma_f32_16x16x32_bf16 v[62:65], v[10:13], v[22:25], 0
	v_mfma_f32_16x16x32_bf16 v[66:69], v[18:21], v[22:25], 0
	v_mfma_f32_16x16x32_bf16 v[70:73], v[26:29], v[22:25], 0
	v_mfma_f32_16x16x32_bf16 v[22:25], v[34:37], v[22:25], 0
	v_mfma_f32_16x16x32_bf16 v[10:13], v[10:13], v[30:33], 0
	v_mfma_f32_16x16x32_bf16 v[18:21], v[18:21], v[30:33], 0
	v_mfma_f32_16x16x32_bf16 v[26:29], v[26:29], v[30:33], 0
	v_mfma_f32_16x16x32_bf16 v[30:33], v[34:37], v[30:33], 0
	v_bitop3_b32 v34, v142, v74, 4 bitop3:0x36
	v_lshlrev_b32_e32 v34, 4, v34
	v_add_u32_e32 v114, v75, v34
	v_add_u32_e32 v115, v76, v34
	ds_read_b128 v[34:37], v114
	ds_read_b128 v[74:77], v115 offset:16384
	ds_read_b128 v[78:81], v114 offset:2048
	ds_read_b128 v[82:85], v115 offset:18432
	ds_read_b128 v[86:89], v114 offset:4096
	ds_read_b128 v[90:93], v115 offset:20480
	ds_read_b128 v[94:97], v114 offset:6144
	ds_read_b128 v[98:101], v115 offset:22528
	s_waitcnt lgkmcnt(6)
	v_mfma_f32_16x16x32_bf16 v[38:41], v[74:77], v[34:37], v[38:41]
	s_waitcnt vmcnt(0)
	s_waitcnt lgkmcnt(0)
	s_barrier
; #define GLDS_STAGE(st, kt_) do { \
;         _Pragma("unroll") for (int i_ = 0; i_ < FI; ++i_) { \
;             glds16(ap + (size_t)(32 * i_) * lda + (kt_) * 64, l3a + (st) + tid * 16 + i_ * 4096); \
;             glds16(bp + (size_t)(32 * i_) * ldb + (kt_) * 64, l3a + (st) + OPB + tid * 16 + i_ * 4096); } } while (0)
; #define GLDS_STAGE(st, kt_) do { \
;         _Pragma("unroll") for (int i_ = 0; i_ < 4; ++i_) { \
;             glds16(ap + (size_t)(64 * i_) * lda + (kt_) * 64, l3a + (st) + tid * 16 + i_ * 8192); \
;             glds16(bp + (size_t)(64 * i_) * ldb + (kt_) * 64, l3a + (st) + 32768 + tid * 16 + i_ * 8192); } } while (0)
; template <int WT, class Epi>
; DEV void gemm_tile(const bf16_t* __restrict__ A, int lda, const bf16_t* __restrict__ Bt, int ldb, int K, unsigned char* lds, const Epi& epi) {
;     ...
;     for (int kt = 0; kt < nk; ++kt) {
;         if (NSTG == 4 && kt + 2 < nk) { if (FI == 2) asm volatile("s_waitcnt vmcnt(8)" ::: "memory"); else asm volatile("s_waitcnt vmcnt(0)" ::: "memory"); }
;         else asm volatile("s_waitcnt vmcnt(0)" ::: "memory");
;         __syncthreads();
;         if (kt + NSTG - 1 < nk) GLDS_STAGE(nxt, kt + NSTG - 1);
; #pragma unroll
;         for (int kh = 0; kh < 2; ++kh) {
;             bf16x8 af[FI], bfr[FI];
;             const int ch = ((kh * 4 + fq) ^ sw) << 4;
; #pragma unroll
;             for (int i = 0; i < FI; ++i) { af[i] = *(const bf16x8*)(lds + cur + aoff + i * 2048 + ch); bfr[i] = *(const bf16x8*)(lds + cur + boff + i * 2048 + ch); }
; #pragma unroll
;             for (int mi = 0; mi < FI; ++mi)
; #pragma unroll
;                 for (int ni = 0; ni < FI; ++ni) acc[mi][ni] = __builtin_amdgcn_mfma_f32_16x16x32_bf16(bfr[ni], af[mi], acc[mi][ni], 0, 0, 0);
;         }
;         nxt = cur; cur += STB; if (cur == NSTG * STB) cur = 0;
;     }
; __global__ void __launch_bounds__(512) hymba_fwd(Params p) {
;     ...
;             for (int t0 = 2 * ob; t0 < NPL; t0 += 2 * no) { const int t = min(t0 + vb, NPL - 1); int nt, mt; tile_map(t, 68, 8, mt, nt); const int g = nt >> 1;
	v_mfma_f32_16x16x32_bf16 v[42:45], v[82:85], v[34:37], v[42:45]
	v_mfma_f32_16x16x32_bf16 v[46:49], v[90:93], v[34:37], v[46:49]
	v_mfma_f32_16x16x32_bf16 v[6:9], v[98:101], v[34:37], v[6:9]
	v_mfma_f32_16x16x32_bf16 v[34:37], v[74:77], v[78:81], v[50:53]
	v_mfma_f32_16x16x32_bf16 v[50:53], v[82:85], v[78:81], v[54:57]
	v_mfma_f32_16x16x32_bf16 v[54:57], v[90:93], v[78:81], v[58:61]
	v_mfma_f32_16x16x32_bf16 v[58:61], v[74:77], v[86:89], v[62:65]
	v_mfma_f32_16x16x32_bf16 v[62:65], v[82:85], v[86:89], v[66:69]
	v_mfma_f32_16x16x32_bf16 v[66:69], v[90:93], v[86:89], v[70:73]
	v_mfma_f32_16x16x32_bf16 v[10:13], v[74:77], v[94:97], v[10:13]
	s_nop 1
	v_lshl_add_u64 v[70:71], v[2:3], 0, s[38:39]
	v_add_u32_e32 v74, s70, v102
	s_mov_b32 s92, m0
	s_mov_b32 m0, s14
	s_nop 0
	global_load_lds_dwordx4 v[70:71], off
	s_mov_b32 m0, s92
	v_lshl_add_u64 v[72:73], v[4:5], 0, s[38:39]
	v_readfirstlane_b32 s14, v74
	s_mov_b32 s92, m0
	s_mov_b32 m0, s14
	s_nop 0
	global_load_lds_dwordx4 v[72:73], off
	s_mov_b32 m0, s92
	v_lshl_add_u64 v[70:71], v[2:3], 0, s[40:41]
	s_mov_b32 s92, m0
	s_mov_b32 m0, s82
	s_nop 0
	global_load_lds_dwordx4 v[70:71], off
	s_mov_b32 m0, s92
	v_lshl_add_u64 v[70:71], v[4:5], 0, s[42:43]
	s_add_i32 s82, s14, 0x1000
	s_mov_b32 s92, m0
	s_mov_b32 m0, s82
	s_nop 0
	global_load_lds_dwordx4 v[70:71], off
	s_mov_b32 m0, s92
	v_lshl_add_u64 v[70:71], v[2:3], 0, s[44:45]
	s_mov_b32 s82, m0
	s_mov_b32 m0, s83
	s_nop 0
	global_load_lds_dwordx4 v[70:71], off
	s_mov_b32 m0, s82
	v_lshl_add_u64 v[70:71], v[4:5], 0, s[46:47]
	s_add_i32 s82, s14, 0x2000
	s_mov_b32 s83, m0
	s_mov_b32 m0, s82
	s_nop 0
	global_load_lds_dwordx4 v[70:71], off
	s_mov_b32 m0, s83
	v_lshl_add_u64 v[70:71], v[2:3], 0, s[48:49]
	s_mov_b32 s82, m0
	s_mov_b32 m0, s84
	s_nop 0
	global_load_lds_dwordx4 v[70:71], off
	s_mov_b32 m0, s82
	v_lshl_add_u64 v[70:71], v[4:5], 0, s[50:51]
	s_addk_i32 s14, 0x3000
	s_mov_b32 s82, m0
	s_mov_b32 m0, s14
	s_nop 0
	global_load_lds_dwordx4 v[70:71], off
	s_mov_b32 m0, s82
	v_mfma_f32_16x16x32_bf16 v[14:17], v[98:101], v[78:81], v[14:17]
	s_cmp_lt_i32 s72, s98
	v_mfma_f32_16x16x32_bf16 v[22:25], v[98:101], v[86:89], v[22:25]
	v_mfma_f32_16x16x32_bf16 v[18:21], v[82:85], v[94:97], v[18:21]
	v_mfma_f32_16x16x32_bf16 v[26:29], v[90:93], v[94:97], v[26:29]
	v_mfma_f32_16x16x32_bf16 v[30:33], v[98:101], v[94:97], v[30:33]
	ds_read_b128 v[70:73], v126 offset:32768
	ds_read_b128 v[74:77], v118 offset:49152
	ds_read_b128 v[78:81], v126 offset:34816
	ds_read_b128 v[82:85], v118 offset:51200
	ds_read_b128 v[86:89], v126 offset:36864
	ds_read_b128 v[90:93], v118 offset:53248
	ds_read_b128 v[94:97], v126 offset:38912
	ds_read_b128 v[98:101], v118 offset:55296
	s_waitcnt lgkmcnt(6)
	v_mfma_f32_16x16x32_bf16 v[38:41], v[74:77], v[70:73], v[38:41]
	s_waitcnt lgkmcnt(4)
	v_mfma_f32_16x16x32_bf16 v[42:45], v[82:85], v[70:73], v[42:45]
	s_waitcnt lgkmcnt(2)
	v_mfma_f32_16x16x32_bf16 v[46:49], v[90:93], v[70:73], v[46:49]
	s_waitcnt lgkmcnt(0)
	v_mfma_f32_16x16x32_bf16 v[6:9], v[98:101], v[70:73], v[6:9]
	v_mfma_f32_16x16x32_bf16 v[34:37], v[74:77], v[78:81], v[34:37]
	v_mfma_f32_16x16x32_bf16 v[50:53], v[82:85], v[78:81], v[50:53]
	v_mfma_f32_16x16x32_bf16 v[54:57], v[90:93], v[78:81], v[54:57]
	v_mfma_f32_16x16x32_bf16 v[14:17], v[98:101], v[78:81], v[14:17]
	v_mfma_f32_16x16x32_bf16 v[58:61], v[74:77], v[86:89], v[58:61]
	v_mfma_f32_16x16x32_bf16 v[62:65], v[82:85], v[86:89], v[62:65]
	v_mfma_f32_16x16x32_bf16 v[66:69], v[90:93], v[86:89], v[66:69]
	v_mfma_f32_16x16x32_bf16 v[22:25], v[98:101], v[86:89], v[22:25]
	v_mfma_f32_16x16x32_bf16 v[10:13], v[74:77], v[94:97], v[10:13]
	v_mfma_f32_16x16x32_bf16 v[18:21], v[82:85], v[94:97], v[18:21]
	v_mfma_f32_16x16x32_bf16 v[26:29], v[90:93], v[94:97], v[26:29]
	v_mfma_f32_16x16x32_bf16 v[30:33], v[98:101], v[94:97], v[30:33]
	ds_read_b128 v[70:73], v114 offset:32768
	ds_read_b128 v[74:77], v115 offset:49152
	ds_read_b128 v[78:81], v114 offset:34816
	ds_read_b128 v[82:85], v115 offset:51200
	ds_read_b128 v[86:89], v114 offset:36864
	ds_read_b128 v[90:93], v115 offset:53248
	ds_read_b128 v[94:97], v114 offset:38912
	ds_read_b128 v[98:101], v115 offset:55296
	s_waitcnt vmcnt(0)
	s_waitcnt lgkmcnt(0)
	v_mfma_f32_16x16x32_bf16 v[38:41], v[74:77], v[70:73], v[38:41]
	s_barrier
; #define GLDS_STAGE(st, kt_) do { \
;         _Pragma("unroll") for (int i_ = 0; i_ < FI; ++i_) { \
;             glds16(ap + (size_t)(32 * i_) * lda + (kt_) * 64, l3a + (st) + tid * 16 + i_ * 4096); \
;             glds16(bp + (size_t)(32 * i_) * ldb + (kt_) * 64, l3a + (st) + OPB + tid * 16 + i_ * 4096); } } while (0)
; #define GLDS_STAGE(st, kt_) do { \
;         _Pragma("unroll") for (int i_ = 0; i_ < 4; ++i_) { \
;             glds16(ap + (size_t)(64 * i_) * lda + (kt_) * 64, l3a + (st) + tid * 16 + i_ * 8192); \
;             glds16(bp + (size_t)(64 * i_) * ldb + (kt_) * 64, l3a + (st) + 32768 + tid * 16 + i_ * 8192); } } while (0)
; template <int WT, class Epi>
; DEV void gemm_tile(const bf16_t* __restrict__ A, int lda, const bf16_t* __restrict__ Bt, int ldb, int K, unsigned char* lds, const Epi& epi) {
;     ...
;     for (int kt = 0; kt < nk; ++kt) {
;         if (NSTG == 4 && kt + 2 < nk) { if (FI == 2) asm volatile("s_waitcnt vmcnt(8)" ::: "memory"); else asm volatile("s_waitcnt vmcnt(0)" ::: "memory"); }
;         else asm volatile("s_waitcnt vmcnt(0)" ::: "memory");
;         __syncthreads();
;         if (kt + NSTG - 1 < nk) GLDS_STAGE(nxt, kt + NSTG - 1);
; #pragma unroll
;         for (int kh = 0; kh < 2; ++kh) {
;             bf16x8 af[FI], bfr[FI];
;             const int ch = ((kh * 4 + fq) ^ sw) << 4;
; #pragma unroll
;             for (int i = 0; i < FI; ++i) { af[i] = *(const bf16x8*)(lds + cur + aoff + i * 2048 + ch); bfr[i] = *(const bf16x8*)(lds + cur + boff + i * 2048 + ch); }
; #pragma unroll
;             for (int mi = 0; mi < FI; ++mi)
; #pragma unroll
;                 for (int ni = 0; ni < FI; ++ni) acc[mi][ni] = __builtin_amdgcn_mfma_f32_16x16x32_bf16(bfr[ni], af[mi], acc[mi][ni], 0, 0, 0);
;         }
;         nxt = cur; cur += STB; if (cur == NSTG * STB) cur = 0;
;     }
	v_mfma_f32_16x16x32_bf16 v[42:45], v[82:85], v[70:73], v[42:45]
	v_mfma_f32_16x16x32_bf16 v[46:49], v[90:93], v[70:73], v[46:49]
	v_mfma_f32_16x16x32_bf16 v[6:9], v[98:101], v[70:73], v[6:9]
	v_lshl_add_u64 v[70:71], v[2:3], 0, s[52:53]
	s_mov_b32 s14, m0
	s_mov_b32 m0, s15
	s_nop 0
	global_load_lds_dwordx4 v[70:71], off
	s_mov_b32 m0, s14
	v_lshl_add_u64 v[72:73], v[4:5], 0, s[52:53]
	s_mov_b32 s14, m0
	s_mov_b32 m0, s85
	s_nop 0
	global_load_lds_dwordx4 v[72:73], off
	s_mov_b32 m0, s14
	v_lshl_add_u64 v[70:71], v[2:3], 0, s[54:55]
	s_mov_b32 s14, m0
	s_mov_b32 m0, s86
	s_nop 0
	global_load_lds_dwordx4 v[70:71], off
	s_mov_b32 m0, s14
	v_lshl_add_u64 v[70:71], v[4:5], 0, s[56:57]
	s_mov_b32 s14, m0
	s_mov_b32 m0, s87
	s_nop 0
	global_load_lds_dwordx4 v[70:71], off
	s_mov_b32 m0, s14
	v_lshl_add_u64 v[70:71], v[2:3], 0, s[58:59]
	s_mov_b32 s14, m0
	s_mov_b32 m0, s88
	s_nop 0
	global_load_lds_dwordx4 v[70:71], off
	s_mov_b32 m0, s14
	v_lshl_add_u64 v[70:71], v[4:5], 0, s[60:61]
	s_mov_b32 s14, m0
	s_mov_b32 m0, s89
	s_nop 0
	global_load_lds_dwordx4 v[70:71], off
	s_mov_b32 m0, s14
	v_lshl_add_u64 v[2:3], v[2:3], 0, s[62:63]
	s_mov_b32 s14, m0
	s_mov_b32 m0, s90
	s_nop 0
	global_load_lds_dwordx4 v[2:3], off
	s_mov_b32 m0, s14
	v_lshl_add_u64 v[2:3], v[4:5], 0, s[64:65]
	s_mov_b32 s14, m0
	s_mov_b32 m0, s91
	s_nop 0
	global_load_lds_dwordx4 v[2:3], off
	s_mov_b32 m0, s14
	v_mfma_f32_16x16x32_bf16 v[34:37], v[74:77], v[78:81], v[34:37]
	v_mfma_f32_16x16x32_bf16 v[50:53], v[82:85], v[78:81], v[50:53]
	v_mfma_f32_16x16x32_bf16 v[54:57], v[90:93], v[78:81], v[54:57]
	v_mfma_f32_16x16x32_bf16 v[14:17], v[98:101], v[78:81], v[14:17]
	v_mfma_f32_16x16x32_bf16 v[58:61], v[74:77], v[86:89], v[58:61]
	v_mfma_f32_16x16x32_bf16 v[62:65], v[82:85], v[86:89], v[62:65]
	v_mfma_f32_16x16x32_bf16 v[66:69], v[90:93], v[86:89], v[66:69]
	v_mfma_f32_16x16x32_bf16 v[22:25], v[98:101], v[86:89], v[22:25]
	v_mfma_f32_16x16x32_bf16 v[10:13], v[74:77], v[94:97], v[10:13]
	v_mfma_f32_16x16x32_bf16 v[18:21], v[82:85], v[94:97], v[18:21]
	v_mfma_f32_16x16x32_bf16 v[26:29], v[90:93], v[94:97], v[26:29]
	v_mfma_f32_16x16x32_bf16 v[30:33], v[98:101], v[94:97], v[30:33]
	ds_read_b128 v[2:5], v126
	ds_read_b128 v[70:73], v118 offset:16384
	ds_read_b128 v[74:77], v126 offset:2048
	ds_read_b128 v[78:81], v118 offset:18432
	ds_read_b128 v[82:85], v126 offset:4096
	ds_read_b128 v[86:89], v118 offset:20480
	ds_read_b128 v[90:93], v126 offset:6144
	ds_read_b128 v[94:97], v118 offset:22528
	s_waitcnt lgkmcnt(6)
	v_mfma_f32_16x16x32_bf16 v[38:41], v[70:73], v[2:5], v[38:41]
	s_waitcnt lgkmcnt(4)
	v_mfma_f32_16x16x32_bf16 v[42:45], v[78:81], v[2:5], v[42:45]
	s_waitcnt lgkmcnt(2)
	v_mfma_f32_16x16x32_bf16 v[46:49], v[86:89], v[2:5], v[46:49]
	s_waitcnt lgkmcnt(0)
	v_mfma_f32_16x16x32_bf16 v[2:5], v[94:97], v[2:5], v[6:9]
	v_mfma_f32_16x16x32_bf16 v[6:9], v[70:73], v[74:77], v[34:37]
	v_mfma_f32_16x16x32_bf16 v[50:53], v[78:81], v[74:77], v[50:53]
	v_mfma_f32_16x16x32_bf16 v[54:57], v[86:89], v[74:77], v[54:57]
	v_mfma_f32_16x16x32_bf16 v[14:17], v[94:97], v[74:77], v[14:17]
	v_mfma_f32_16x16x32_bf16 v[58:61], v[70:73], v[82:85], v[58:61]
	v_mfma_f32_16x16x32_bf16 v[62:65], v[78:81], v[82:85], v[62:65]
	v_mfma_f32_16x16x32_bf16 v[66:69], v[86:89], v[82:85], v[66:69]
	v_mfma_f32_16x16x32_bf16 v[74:77], v[94:97], v[82:85], v[22:25]
	v_mfma_f32_16x16x32_bf16 v[10:13], v[70:73], v[90:93], v[10:13]
	v_mfma_f32_16x16x32_bf16 v[78:81], v[78:81], v[90:93], v[18:21]
	v_mfma_f32_16x16x32_bf16 v[82:85], v[86:89], v[90:93], v[26:29]
	v_mfma_f32_16x16x32_bf16 v[86:89], v[94:97], v[90:93], v[30:33]
	s_nop 2
	ds_read_b128 v[30:33], v114
	ds_read_b128 v[90:93], v115 offset:16384
	ds_read_b128 v[70:73], v114 offset:2048
	ds_read_b128 v[94:97], v115 offset:18432
	ds_read_b128 v[98:101], v114 offset:4096
	ds_read_b128 v[102:105], v115 offset:20480
	ds_read_b128 v[106:109], v114 offset:6144
	ds_read_b128 v[110:113], v115 offset:22528
	s_waitcnt vmcnt(0)
	s_waitcnt lgkmcnt(0)
	v_mfma_f32_16x16x32_bf16 v[18:21], v[90:93], v[30:33], v[38:41]
	s_barrier
	v_mfma_f32_16x16x32_bf16 v[22:25], v[94:97], v[30:33], v[42:45]
	v_mfma_f32_16x16x32_bf16 v[26:29], v[102:105], v[30:33], v[46:49]
	v_mfma_f32_16x16x32_bf16 v[30:33], v[110:113], v[30:33], v[2:5]
	v_mfma_f32_16x16x32_bf16 v[34:37], v[90:93], v[70:73], v[6:9]
	v_mfma_f32_16x16x32_bf16 v[38:41], v[94:97], v[70:73], v[50:53]
	v_mfma_f32_16x16x32_bf16 v[50:53], v[102:105], v[70:73], v[54:57]
	v_mfma_f32_16x16x32_bf16 v[54:57], v[110:113], v[70:73], v[14:17]
	v_mfma_f32_16x16x32_bf16 v[58:61], v[90:93], v[98:101], v[58:61]
	v_mfma_f32_16x16x32_bf16 v[62:65], v[94:97], v[98:101], v[62:65]
	v_mfma_f32_16x16x32_bf16 v[66:69], v[102:105], v[98:101], v[66:69]
	v_mfma_f32_16x16x32_bf16 v[70:73], v[110:113], v[98:101], v[74:77]
	v_mfma_f32_16x16x32_bf16 v[74:77], v[90:93], v[106:109], v[10:13]
	v_mfma_f32_16x16x32_bf16 v[78:81], v[94:97], v[106:109], v[78:81]
	v_mfma_f32_16x16x32_bf16 v[82:85], v[102:105], v[106:109], v[82:85]
	v_mfma_f32_16x16x32_bf16 v[86:89], v[110:113], v[106:109], v[86:89]
	ds_read_b128 v[2:5], v115 offset:55296
	ds_read_b128 v[42:45], v114 offset:38912
	ds_read_b128 v[6:9], v115 offset:53248
	ds_read_b128 v[14:17], v114 offset:36864
	ds_read_b128 v[10:13], v115 offset:51200
	ds_read_b128 v[90:93], v114 offset:34816
	ds_read_b128 v[46:49], v115 offset:49152
	ds_read_b128 v[94:97], v114 offset:32768
	ds_read_b128 v[98:101], v118 offset:55296
	ds_read_b128 v[102:105], v126 offset:38912
	ds_read_b128 v[106:109], v118 offset:53248
	ds_read_b128 v[114:117], v126 offset:36864
	ds_read_b128 v[110:113], v118 offset:51200
	ds_read_b128 v[122:125], v126 offset:34816
	ds_read_b128 v[118:121], v118 offset:49152
	ds_read_b128 v[126:129], v126 offset:32768
	s_waitcnt lgkmcnt(0)
	s_barrier
; template <int WT, class Epi>
; DEV void gemm_tile(const bf16_t* __restrict__ A, int lda, const bf16_t* __restrict__ Bt, int ldb, int K, unsigned char* lds, const Epi& epi) {
;     ...
;                 const int row = wr * WT + mi * 16 + fr, col = wc * WT + ni * 16 + fq * 4;
;     DEV f32x4 xform(int r, int c, f32x4 v) const {
;         const int row = m0 + r, col = n0 + c;
;         const uint2 z = *(const uint2*)(proj + (size_t)row * NPJ + C_ZB + col);
;         const f32x4 s = *(const f32x4*)(scale + col);
	v_lshl_or_b32 v184, v142, 2, v143
	v_add_u32_e32 v176, s81, v130
	v_or_b32_e32 v178, s68, v184
	v_mad_i64_i32 v[176:177], s[96:97], v176, s79, v[172:173]
	v_ashrrev_i32_e32 v179, 31, v178
	v_lshl_add_u64 v[182:183], v[176:177], 0, s[66:67]
	v_lshlrev_b64 v[180:181], 1, v[178:179]
	v_lshl_add_u64 v[176:177], v[182:183], 0, v[180:181]
	global_load_dwordx2 v[192:193], v[176:177], off
	v_lshl_or_b32 v180, v142, 2, v143
	v_or_b32_e32 v176, s68, v180
	v_ashrrev_i32_e32 v177, 31, v176
	v_lshl_add_u64 v[178:179], v[176:177], 2, s[4:5]
	global_load_dwordx4 v[194:197], v[178:179], off
	v_lshl_or_b32 v186, v142, 2, v143
	v_add_u32_e32 v176, s81, v130
	v_mad_i64_i32 v[176:177], s[96:97], v176, s79, v[172:173]
	v_lshl_add_u64 v[184:185], v[176:177], 0, s[66:67]
	v_or_b32_e32 v183, 16, v186
	v_or_b32_e32 v178, s68, v183
	v_ashrrev_i32_e32 v179, 31, v178
	v_lshlrev_b64 v[180:181], 1, v[178:179]
	v_lshl_add_u64 v[178:179], v[184:185], 0, v[180:181]
	global_load_dwordx2 v[198:199], v[178:179], off
	v_lshl_or_b32 v182, v142, 2, v143
	v_or_b32_e32 v176, s68, v182
	v_mov_b32_e32 v177, s69
	v_lshl_add_u64 v[180:181], v[176:177], 2, s[4:5]
	global_load_dwordx4 v[200:203], v[180:181], off offset:64
	v_lshl_or_b32 v184, v142, 2, v143
	v_add_u32_e32 v176, s81, v130
	v_mad_i64_i32 v[176:177], s[96:97], v176, s79, v[172:173]
	v_lshl_add_u64 v[182:183], v[176:177], 0, s[66:67]
	v_or_b32_e32 v185, 32, v184
	v_or_b32_e32 v178, s68, v185
	v_ashrrev_i32_e32 v179, 31, v178
	v_lshlrev_b64 v[178:179], 1, v[178:179]
	v_lshl_add_u64 v[180:181], v[182:183], 0, v[178:179]
	global_load_dwordx2 v[204:205], v[180:181], off
	v_lshl_or_b32 v180, v142, 2, v143
	v_or_b32_e32 v176, s68, v180
	v_mov_b32_e32 v177, s69
	v_lshl_add_u64 v[178:179], v[176:177], 2, s[4:5]
	global_load_dwordx4 v[206:209], v[178:179], off offset:128
	v_lshl_or_b32 v186, v142, 2, v143
	v_add_u32_e32 v176, s81, v130
	v_mad_i64_i32 v[176:177], s[96:97], v176, s79, v[172:173]
	v_lshl_add_u64 v[184:185], v[176:177], 0, s[66:67]
	v_or_b32_e32 v181, 48, v186
	v_or_b32_e32 v178, s68, v181
	v_ashrrev_i32_e32 v179, 31, v178
	v_lshlrev_b64 v[178:179], 1, v[178:179]
	v_lshl_add_u64 v[182:183], v[184:185], 0, v[178:179]
	global_load_dwordx2 v[210:211], v[182:183], off
	v_lshl_or_b32 v180, v142, 2, v143
	v_or_b32_e32 v176, s68, v180
	v_mov_b32_e32 v177, s69
	v_lshl_add_u64 v[178:179], v[176:177], 2, s[4:5]
	global_load_dwordx4 v[212:215], v[178:179], off offset:192
	v_lshl_or_b32 v186, v142, 2, v143
	v_or_b32_e32 v176, s68, v186
	v_ashrrev_i32_e32 v177, 31, v176
	v_lshlrev_b64 v[182:183], 1, v[176:177]
	v_or_b32_e32 v179, 16, v130
	v_add_u32_e32 v179, s81, v179
	v_mad_i64_i32 v[180:181], s[96:97], v179, s79, v[172:173]
	v_lshl_add_u64 v[180:181], v[180:181], 0, s[66:67]
	v_lshl_add_u64 v[184:185], v[180:181], 0, v[182:183]
	global_load_dwordx2 v[216:217], v[184:185], off
	v_lshl_or_b32 v188, v142, 2, v143
	v_or_b32_e32 v187, 16, v188
	v_or_b32_e32 v178, s68, v187
	v_ashrrev_i32_e32 v179, 31, v178
	v_lshlrev_b64 v[184:185], 1, v[178:179]
	v_or_b32_e32 v181, 16, v130
	v_add_u32_e32 v181, s81, v181
	v_mad_i64_i32 v[182:183], s[96:97], v181, s79, v[172:173]
	v_lshl_add_u64 v[182:183], v[182:183], 0, s[66:67]
	v_lshl_add_u64 v[176:177], v[182:183], 0, v[184:185]
	global_load_dwordx2 v[218:219], v[176:177], off
	v_lshl_or_b32 v184, v142, 2, v143
	v_or_b32_e32 v185, 32, v184
	v_or_b32_e32 v182, s68, v185
	v_ashrrev_i32_e32 v183, 31, v182
	v_lshlrev_b64 v[182:183], 1, v[182:183]
	v_or_b32_e32 v179, 16, v130
	v_add_u32_e32 v179, s81, v179
	v_mad_i64_i32 v[180:181], s[96:97], v179, s79, v[172:173]
	v_lshl_add_u64 v[180:181], v[180:181], 0, s[66:67]
	v_lshl_add_u64 v[176:177], v[180:181], 0, v[182:183]
	global_load_dwordx2 v[220:221], v[176:177], off
	v_lshl_or_b32 v186, v142, 2, v143
	v_or_b32_e32 v185, 48, v186
	v_or_b32_e32 v182, s68, v185
	v_ashrrev_i32_e32 v183, 31, v182
	v_lshlrev_b64 v[182:183], 1, v[182:183]
	v_or_b32_e32 v179, 16, v130
	v_add_u32_e32 v179, s81, v179
	v_mad_i64_i32 v[180:181], s[96:97], v179, s79, v[172:173]
	v_lshl_add_u64 v[180:181], v[180:181], 0, s[66:67]
	v_lshl_add_u64 v[176:177], v[180:181], 0, v[182:183]
	global_load_dwordx2 v[222:223], v[176:177], off
	v_lshl_or_b32 v184, v142, 2, v143
	v_or_b32_e32 v180, s68, v184
	v_ashrrev_i32_e32 v181, 31, v180
	v_lshlrev_b64 v[182:183], 1, v[180:181]
	v_or_b32_e32 v176, 32, v130
	v_add_u32_e32 v176, s81, v176
	v_mad_i64_i32 v[176:177], s[96:97], v176, s79, v[172:173]
	v_lshl_add_u64 v[178:179], v[176:177], 0, s[66:67]
	v_lshl_add_u64 v[176:177], v[178:179], 0, v[182:183]
	global_load_dwordx2 v[224:225], v[176:177], off
	v_lshl_or_b32 v188, v142, 2, v143
	v_or_b32_e32 v187, 16, v188
	v_or_b32_e32 v182, s68, v187
	v_ashrrev_i32_e32 v183, 31, v182
	v_lshlrev_b64 v[184:185], 1, v[182:183]
	v_or_b32_e32 v178, 32, v130
	v_add_u32_e32 v178, s81, v178
	v_mad_i64_i32 v[178:179], s[96:97], v178, s79, v[172:173]
	v_lshl_add_u64 v[180:181], v[178:179], 0, s[66:67]
	v_lshl_add_u64 v[176:177], v[180:181], 0, v[184:185]
	global_load_dwordx2 v[226:227], v[176:177], off
	v_lshl_or_b32 v184, v142, 2, v143
	v_or_b32_e32 v185, 32, v184
; template <int WT, class Epi>
; DEV void gemm_tile(const bf16_t* __restrict__ A, int lda, const bf16_t* __restrict__ Bt, int ldb, int K, unsigned char* lds, const Epi& epi) {
;     ...
; #pragma unroll
;         for (int kh = 0; kh < 2; ++kh) {
;             bf16x8 af[FI], bfr[FI];
;             const int ch = ((kh * 4 + fq) ^ sw) << 4;
; #pragma unroll
;             for (int i = 0; i < FI; ++i) { af[i] = *(const bf16x8*)(lds + cur + aoff + i * 2048 + ch); bfr[i] = *(const bf16x8*)(lds + cur + boff + i * 2048 + ch); }
; #pragma unroll
;             for (int mi = 0; mi < FI; ++mi)
; #pragma unroll
;                 for (int ni = 0; ni < FI; ++ni) acc[mi][ni] = __builtin_amdgcn_mfma_f32_16x16x32_bf16(bfr[ni], af[mi], acc[mi][ni], 0, 0, 0);
;         }
;     ...
;                 const int row = wr * WT + mi * 16 + fr, col = wc * WT + ni * 16 + fq * 4;
;     DEV f32x4 xform(int r, int c, f32x4 v) const {
;     ...
;         const uint2 z = *(const uint2*)(proj + (size_t)row * NPJ + C_ZB + col);
	v_or_b32_e32 v182, s68, v185
	v_ashrrev_i32_e32 v183, 31, v182
	v_lshlrev_b64 v[182:183], 1, v[182:183]
	v_or_b32_e32 v178, 32, v130
	v_add_u32_e32 v178, s81, v178
	v_mad_i64_i32 v[178:179], s[96:97], v178, s79, v[172:173]
	v_lshl_add_u64 v[180:181], v[178:179], 0, s[66:67]
	v_lshl_add_u64 v[176:177], v[180:181], 0, v[182:183]
	global_load_dwordx2 v[228:229], v[176:177], off
	v_lshl_or_b32 v186, v142, 2, v143
	v_or_b32_e32 v185, 48, v186
	v_or_b32_e32 v182, s68, v185
	v_ashrrev_i32_e32 v183, 31, v182
	v_lshlrev_b64 v[182:183], 1, v[182:183]
	v_or_b32_e32 v178, 32, v130
	v_add_u32_e32 v178, s81, v178
	v_mad_i64_i32 v[178:179], s[96:97], v178, s79, v[172:173]
	v_lshl_add_u64 v[180:181], v[178:179], 0, s[66:67]
	v_lshl_add_u64 v[176:177], v[180:181], 0, v[182:183]
	global_load_dwordx2 v[230:231], v[176:177], off
	v_lshl_or_b32 v184, v142, 2, v143
	v_or_b32_e32 v180, s68, v184
	v_ashrrev_i32_e32 v181, 31, v180
	v_lshlrev_b64 v[182:183], 1, v[180:181]
	v_or_b32_e32 v176, 48, v130
	v_add_u32_e32 v176, s81, v176
	v_mad_i64_i32 v[176:177], s[96:97], v176, s79, v[172:173]
	v_lshl_add_u64 v[178:179], v[176:177], 0, s[66:67]
	v_lshl_add_u64 v[176:177], v[178:179], 0, v[182:183]
	global_load_dwordx2 v[232:233], v[176:177], off
	v_lshl_or_b32 v188, v142, 2, v143
	v_or_b32_e32 v187, 16, v188
	v_or_b32_e32 v182, s68, v187
	v_ashrrev_i32_e32 v183, 31, v182
	v_lshlrev_b64 v[184:185], 1, v[182:183]
	v_or_b32_e32 v178, 48, v130
	v_add_u32_e32 v178, s81, v178
	v_mad_i64_i32 v[178:179], s[96:97], v178, s79, v[172:173]
	v_lshl_add_u64 v[180:181], v[178:179], 0, s[66:67]
	v_lshl_add_u64 v[176:177], v[180:181], 0, v[184:185]
	global_load_dwordx2 v[234:235], v[176:177], off
	v_lshl_or_b32 v184, v142, 2, v143
	v_or_b32_e32 v185, 32, v184
	v_or_b32_e32 v182, s68, v185
	v_ashrrev_i32_e32 v183, 31, v182
	v_lshlrev_b64 v[182:183], 1, v[182:183]
	v_or_b32_e32 v178, 48, v130
	v_add_u32_e32 v178, s81, v178
	v_mad_i64_i32 v[178:179], s[96:97], v178, s79, v[172:173]
	v_lshl_add_u64 v[180:181], v[178:179], 0, s[66:67]
	v_lshl_add_u64 v[176:177], v[180:181], 0, v[182:183]
	global_load_dwordx2 v[236:237], v[176:177], off
	v_lshl_or_b32 v186, v142, 2, v143
	v_or_b32_e32 v185, 48, v186
	v_or_b32_e32 v182, s68, v185
	v_ashrrev_i32_e32 v183, 31, v182
	v_lshlrev_b64 v[182:183], 1, v[182:183]
	v_or_b32_e32 v178, 48, v130
	v_add_u32_e32 v178, s81, v178
	v_mad_i64_i32 v[178:179], s[96:97], v178, s79, v[172:173]
	v_lshl_add_u64 v[180:181], v[178:179], 0, s[66:67]
	v_lshl_add_u64 v[176:177], v[180:181], 0, v[182:183]
	global_load_dwordx2 v[238:239], v[176:177], off
	v_mfma_f32_16x16x32_bf16 v[18:21], v[118:121], v[126:129], v[18:21]
	v_mfma_f32_16x16x32_bf16 v[22:25], v[110:113], v[126:129], v[22:25]
	v_mfma_f32_16x16x32_bf16 v[26:29], v[106:109], v[126:129], v[26:29]
	v_mfma_f32_16x16x32_bf16 v[30:33], v[98:101], v[126:129], v[30:33]
	v_mfma_f32_16x16x32_bf16 v[34:37], v[118:121], v[122:125], v[34:37]
	v_mfma_f32_16x16x32_bf16 v[38:41], v[110:113], v[122:125], v[38:41]
	v_mfma_f32_16x16x32_bf16 v[126:129], v[106:109], v[122:125], v[50:53]
	v_mfma_f32_16x16x32_bf16 v[122:125], v[98:101], v[122:125], v[54:57]
	v_mfma_f32_16x16x32_bf16 v[144:147], v[118:121], v[114:117], v[58:61]
	v_mfma_f32_16x16x32_bf16 v[148:151], v[110:113], v[114:117], v[62:65]
	v_mfma_f32_16x16x32_bf16 v[66:69], v[106:109], v[114:117], v[66:69]
	v_mfma_f32_16x16x32_bf16 v[70:73], v[98:101], v[114:117], v[70:73]
	v_mfma_f32_16x16x32_bf16 v[74:77], v[118:121], v[102:105], v[74:77]
	v_mfma_f32_16x16x32_bf16 v[78:81], v[110:113], v[102:105], v[78:81]
	v_mfma_f32_16x16x32_bf16 v[82:85], v[106:109], v[102:105], v[82:85]
	v_mfma_f32_16x16x32_bf16 v[86:89], v[98:101], v[102:105], v[86:89]
	v_mfma_f32_16x16x32_bf16 v[98:101], v[46:49], v[94:97], v[18:21]
	v_mfma_f32_16x16x32_bf16 v[102:105], v[10:13], v[94:97], v[22:25]
	v_mfma_f32_16x16x32_bf16 v[62:65], v[6:9], v[94:97], v[26:29]
	v_mfma_f32_16x16x32_bf16 v[58:61], v[2:5], v[94:97], v[30:33]
	v_mfma_f32_16x16x32_bf16 v[54:57], v[46:49], v[90:93], v[34:37]
	v_mfma_f32_16x16x32_bf16 v[50:53], v[10:13], v[90:93], v[38:41]
	v_mfma_f32_16x16x32_bf16 v[38:41], v[6:9], v[90:93], v[126:129]
	v_mfma_f32_16x16x32_bf16 v[34:37], v[2:5], v[90:93], v[122:125]
	v_lshl_add_u32 v90, v130, 8, s70
	v_mfma_f32_16x16x32_bf16 v[30:33], v[46:49], v[14:17], v[144:147]
	v_mfma_f32_16x16x32_bf16 v[26:29], v[10:13], v[14:17], v[148:151]
	v_mfma_f32_16x16x32_bf16 v[22:25], v[6:9], v[14:17], v[66:69]
	v_mfma_f32_16x16x32_bf16 v[18:21], v[2:5], v[14:17], v[70:73]
	v_mfma_f32_16x16x32_bf16 v[14:17], v[46:49], v[42:45], v[74:77]
	v_mfma_f32_16x16x32_bf16 v[10:13], v[10:13], v[42:45], v[78:81]
	v_mfma_f32_16x16x32_bf16 v[6:9], v[6:9], v[42:45], v[82:85]
	v_mfma_f32_16x16x32_bf16 v[2:5], v[2:5], v[42:45], v[86:89]
	v_lshrrev_b32_e32 v42, 1, v137
	s_nop 1
	v_lshl_or_b32 v88, v142, 2, v143
	v_and_b32_e32 v89, 8, v42
	v_add_u32_e32 v42, s81, v130
	v_or_b32_e32 v46, s68, v88
	v_mad_i64_i32 v[42:43], s[82:83], v42, s79, v[172:173]
	v_ashrrev_i32_e32 v47, 31, v46
	v_lshl_add_u64 v[82:83], v[42:43], 0, s[66:67]
	v_lshlrev_b64 v[68:69], 1, v[46:47]
	v_lshl_add_u64 v[42:43], v[82:83], 0, v[68:69]

;     DEV f32x4 xform(int r, int c, f32x4 v) const {
;     ...
;         const f32x4 s = *(const f32x4*)(scale + col);
	v_lshl_add_u64 v[70:71], v[46:47], 2, s[4:5]

; DEV float bflo(unsigned u) { return __uint_as_float(u << 16); }
; DEV float bfhi(unsigned u) { return __uint_as_float(u & 0xffff0000u); }
; DEV float silu_f(float x) { return x / (1.f + __expf(-x)); }
;     DEV f32x4 xform(int r, int c, f32x4 v) const {
;     ...
;         o[0] = v[0] * s[0] * silu_f(bflo(z.x)); o[1] = v[1] * s[1] * silu_f(bfhi(z.x));
	s_waitcnt vmcnt(1)
	v_lshlrev_b32_e32 v47, 16, v192
	v_and_b32_e32 v48, 0xffff0000, v192
	v_mul_f32_e32 v66, 0xbfb8aa3b, v47
	v_mul_f32_e32 v67, 0xbfb8aa3b, v48
	v_exp_f32_e32 v66, v66
	v_exp_f32_e32 v67, v67
	s_waitcnt vmcnt(0)
	v_pk_mul_f32 v[74:75], v[98:99], v[194:195]
	v_pk_mul_f32 v[72:73], v[100:101], v[196:197]
	v_pk_mul_f32 v[42:43], v[54:55], v[194:195]
	v_pk_add_f32 v[66:67], v[66:67], 1.0 op_sel_hi:[1,0]
	v_pk_mul_f32 v[44:45], v[56:57], v[196:197]


; DEV float silu_f(float x) { return x / (1.f + __expf(-x)); }
	s_nop 0


; DEV float silu_f(float x) { return x / (1.f + __expf(-x)); }
	v_rcp_f32_e32 v76, v67
	s_nop 0
	v_mul_f32_e32 v67, v48, v76


; DEV float silu_f(float x) { return x / (1.f + __expf(-x)); }
	s_nop 0


; DEV unsigned cvt_pk_bf16(float lo, float hi) { const f32x2_t v = {lo, hi}; const bf16x2_t b = __builtin_convertvector(v, bf16x2_t); return __builtin_bit_cast(unsigned, b); }
; DEV float bflo(unsigned u) { return __uint_as_float(u << 16); }
; DEV float bfhi(unsigned u) { return __uint_as_float(u & 0xffff0000u); }
; DEV float silu_f(float x) { return x / (1.f + __expf(-x)); }
; template <int WT, class Epi>
; DEV void gemm_tile(const bf16_t* __restrict__ A, int lda, const bf16_t* __restrict__ Bt, int ldb, int K, unsigned char* lds, const Epi& epi) {
;     ...
;                 uint2 w; w.x = cvt_pk_bf16(v[0], v[1]); w.y = cvt_pk_bf16(v[2], v[3]);
;     DEV f32x4 xform(int r, int c, f32x4 v) const {
;     ...
;         o[0] = v[0] * s[0] * silu_f(bflo(z.x)); o[1] = v[1] * s[1] * silu_f(bfhi(z.x));
;         o[2] = v[2] * s[2] * silu_f(bflo(z.y)); o[3] = v[3] * s[3] * silu_f(bfhi(z.y));
	v_rcp_f32_e32 v48, v66
	s_nop 0
	v_mul_f32_e32 v66, v47, v48
	v_pk_mul_f32 v[66:67], v[74:75], v[66:67]
	v_lshlrev_b32_e32 v47, 16, v193
	v_and_b32_e32 v74, 0xffff0000, v193
	v_mul_f32_e32 v48, 0xbfb8aa3b, v47
	v_mul_f32_e32 v49, 0xbfb8aa3b, v74
	v_exp_f32_e32 v48, v48
	v_exp_f32_e32 v49, v49
	v_cvt_pk_bf16_f32 v66, v66, v67
	v_pk_add_f32 v[48:49], v[48:49], 1.0 op_sel_hi:[1,0]
	s_nop 0


; DEV float silu_f(float x) { return x / (1.f + __expf(-x)); }
	s_nop 0


; DEV float silu_f(float x) { return x / (1.f + __expf(-x)); }
	v_rcp_f32_e32 v75, v49
	s_nop 0
	v_mul_f32_e32 v49, v74, v75


; DEV float silu_f(float x) { return x / (1.f + __expf(-x)); }
	s_nop 0


; DEV unsigned cvt_pk_bf16(float lo, float hi) { const f32x2_t v = {lo, hi}; const bf16x2_t b = __builtin_convertvector(v, bf16x2_t); return __builtin_bit_cast(unsigned, b); }
; DEV float bflo(unsigned u) { return __uint_as_float(u << 16); }
; DEV float bfhi(unsigned u) { return __uint_as_float(u & 0xffff0000u); }
; DEV float silu_f(float x) { return x / (1.f + __expf(-x)); }
; template <int WT, class Epi>
; DEV void gemm_tile(const bf16_t* __restrict__ A, int lda, const bf16_t* __restrict__ Bt, int ldb, int K, unsigned char* lds, const Epi& epi) {
;     ...
;                 uint2 w; w.x = cvt_pk_bf16(v[0], v[1]); w.y = cvt_pk_bf16(v[2], v[3]);
;     DEV f32x4 xform(int r, int c, f32x4 v) const {
;     ...
;         const uint2 z = *(const uint2*)(proj + (size_t)row * NPJ + C_ZB + col);
;     ...
;         o[2] = v[2] * s[2] * silu_f(bflo(z.y)); o[3] = v[3] * s[3] * silu_f(bfhi(z.y));
	v_rcp_f32_e32 v74, v48
	s_nop 0
	v_mul_f32_e32 v48, v47, v74
	v_pk_mul_f32 v[48:49], v[72:73], v[48:49]
	v_or_b32_e32 v77, 16, v88
	v_cvt_pk_bf16_f32 v67, v48, v49
	v_or_b32_e32 v48, s68, v77
	v_ashrrev_i32_e32 v49, 31, v48
	v_lshlrev_b64 v[72:73], 1, v[48:49]
	v_lshl_add_u64 v[48:49], v[82:83], 0, v[72:73]

; template <int WT, class Epi>
; DEV void gemm_tile(const bf16_t* __restrict__ A, int lda, const bf16_t* __restrict__ Bt, int ldb, int K, unsigned char* lds, const Epi& epi) {
;     ...
;                 *(uint2*)(lds + row * RB + ((((col >> 3) ^ (row & (CPR - 1))) << 4) | (((col >> 2) & 1) << 3))) = w;
	v_lshrrev_b32_e32 v47, 3, v88
	v_bitop3_b32 v47, v47, v137, 15 bitop3:0x78
	v_lshl_or_b32 v76, v47, 4, v89
	v_add_u32_e32 v47, v90, v76
	ds_write_b64 v47, v[66:67]
	v_mov_b32_e32 v47, s69
	v_lshl_add_u64 v[66:67], v[46:47], 2, s[4:5]

; DEV float bflo(unsigned u) { return __uint_as_float(u << 16); }
; DEV float bfhi(unsigned u) { return __uint_as_float(u & 0xffff0000u); }
; DEV float silu_f(float x) { return x / (1.f + __expf(-x)); }
;     DEV f32x4 xform(int r, int c, f32x4 v) const {
;     ...
;         o[0] = v[0] * s[0] * silu_f(bflo(z.x)); o[1] = v[1] * s[1] * silu_f(bfhi(z.x));
	s_waitcnt vmcnt(1)
	v_lshlrev_b32_e32 v86, 16, v198
	v_and_b32_e32 v74, 0xffff0000, v198
	v_mul_f32_e32 v78, 0xbfb8aa3b, v86
	v_mul_f32_e32 v79, 0xbfb8aa3b, v74
	v_exp_f32_e32 v78, v78
	v_exp_f32_e32 v79, v79
	s_waitcnt vmcnt(0)
	v_pk_mul_f32 v[84:85], v[102:103], v[200:201]
	v_pk_add_f32 v[78:79], v[78:79], 1.0 op_sel_hi:[1,0]
	v_pk_mul_f32 v[80:81], v[104:105], v[202:203]


; DEV float bflo(unsigned u) { return __uint_as_float(u << 16); }
; DEV float bfhi(unsigned u) { return __uint_as_float(u & 0xffff0000u); }
; DEV float silu_f(float x) { return x / (1.f + __expf(-x)); }
;     DEV f32x4 xform(int r, int c, f32x4 v) const {
;     ...
;         o[0] = v[0] * s[0] * silu_f(bflo(z.x)); o[1] = v[1] * s[1] * silu_f(bfhi(z.x));
;         o[2] = v[2] * s[2] * silu_f(bflo(z.y)); o[3] = v[3] * s[3] * silu_f(bfhi(z.y));
	v_pk_mul_f32 v[46:47], v[50:51], v[200:201]
	v_pk_mul_f32 v[48:49], v[52:53], v[202:203]


; DEV float silu_f(float x) { return x / (1.f + __expf(-x)); }
	v_rcp_f32_e32 v87, v79
	s_nop 0
	v_mul_f32_e32 v79, v74, v87


; DEV float silu_f(float x) { return x / (1.f + __expf(-x)); }
	s_nop 0


; DEV unsigned cvt_pk_bf16(float lo, float hi) { const f32x2_t v = {lo, hi}; const bf16x2_t b = __builtin_convertvector(v, bf16x2_t); return __builtin_bit_cast(unsigned, b); }
; DEV float bflo(unsigned u) { return __uint_as_float(u << 16); }
; DEV float bfhi(unsigned u) { return __uint_as_float(u & 0xffff0000u); }
; DEV float silu_f(float x) { return x / (1.f + __expf(-x)); }
; template <int WT, class Epi>
; DEV void gemm_tile(const bf16_t* __restrict__ A, int lda, const bf16_t* __restrict__ Bt, int ldb, int K, unsigned char* lds, const Epi& epi) {
;     ...
;                 uint2 w; w.x = cvt_pk_bf16(v[0], v[1]); w.y = cvt_pk_bf16(v[2], v[3]);
;     DEV f32x4 xform(int r, int c, f32x4 v) const {
;     ...
;         o[0] = v[0] * s[0] * silu_f(bflo(z.x)); o[1] = v[1] * s[1] * silu_f(bfhi(z.x));
;         o[2] = v[2] * s[2] * silu_f(bflo(z.y)); o[3] = v[3] * s[3] * silu_f(bfhi(z.y));
	v_rcp_f32_e32 v74, v78
	s_nop 0
	v_mul_f32_e32 v78, v86, v74
	v_pk_mul_f32 v[78:79], v[84:85], v[78:79]
	v_lshlrev_b32_e32 v84, 16, v199
	v_and_b32_e32 v85, 0xffff0000, v199
	v_mul_f32_e32 v74, 0xbfb8aa3b, v84
	v_mul_f32_e32 v75, 0xbfb8aa3b, v85
	v_exp_f32_e32 v74, v74
	v_exp_f32_e32 v75, v75
	v_cvt_pk_bf16_f32 v78, v78, v79
	v_pk_add_f32 v[74:75], v[74:75], 1.0 op_sel_hi:[1,0]
	s_nop 0


; DEV float silu_f(float x) { return x / (1.f + __expf(-x)); }
	s_nop 0


; DEV float silu_f(float x) { return x / (1.f + __expf(-x)); }
	v_rcp_f32_e32 v86, v75
	s_nop 0
	v_mul_f32_e32 v75, v85, v86


; DEV float silu_f(float x) { return x / (1.f + __expf(-x)); }
	s_nop 0


; DEV unsigned cvt_pk_bf16(float lo, float hi) { const f32x2_t v = {lo, hi}; const bf16x2_t b = __builtin_convertvector(v, bf16x2_t); return __builtin_bit_cast(unsigned, b); }
; DEV float bflo(unsigned u) { return __uint_as_float(u << 16); }
; DEV float bfhi(unsigned u) { return __uint_as_float(u & 0xffff0000u); }
; DEV float silu_f(float x) { return x / (1.f + __expf(-x)); }
; template <int WT, class Epi>
; DEV void gemm_tile(const bf16_t* __restrict__ A, int lda, const bf16_t* __restrict__ Bt, int ldb, int K, unsigned char* lds, const Epi& epi) {
;     ...
;                 uint2 w; w.x = cvt_pk_bf16(v[0], v[1]); w.y = cvt_pk_bf16(v[2], v[3]);
;                 *(uint2*)(lds + row * RB + ((((col >> 3) ^ (row & (CPR - 1))) << 4) | (((col >> 2) & 1) << 3))) = w;
;     DEV f32x4 xform(int r, int c, f32x4 v) const {
;     ...
;         o[2] = v[2] * s[2] * silu_f(bflo(z.y)); o[3] = v[3] * s[3] * silu_f(bfhi(z.y));
	v_rcp_f32_e32 v85, v74
	s_nop 0
	v_mul_f32_e32 v74, v84, v85
	v_pk_mul_f32 v[74:75], v[80:81], v[74:75]
	v_or_b32_e32 v91, 32, v88
	v_cvt_pk_bf16_f32 v79, v74, v75
	v_lshrrev_b32_e32 v74, 3, v77
	v_bitop3_b32 v74, v74, v137, 15 bitop3:0x78
	v_lshl_or_b32 v77, v74, 4, v89
	v_add_u32_e32 v74, v90, v77
	ds_write_b64 v74, v[78:79]
	v_or_b32_e32 v74, s68, v91
	v_ashrrev_i32_e32 v75, 31, v74
	v_lshlrev_b64 v[74:75], 1, v[74:75]
	v_lshl_add_u64 v[78:79], v[82:83], 0, v[74:75]

; DEV float silu_f(float x) { return x / (1.f + __expf(-x)); }
	s_nop 0

; DEV float bflo(unsigned u) { return __uint_as_float(u << 16); }
; DEV float bfhi(unsigned u) { return __uint_as_float(u & 0xffff0000u); }
; DEV float silu_f(float x) { return x / (1.f + __expf(-x)); }
;     DEV f32x4 xform(int r, int c, f32x4 v) const {
;     ...
;         o[0] = v[0] * s[0] * silu_f(bflo(z.x)); o[1] = v[1] * s[1] * silu_f(bfhi(z.x));
	s_waitcnt vmcnt(1)
	v_lshlrev_b32_e32 v92, 16, v204
	v_and_b32_e32 v84, 0xffff0000, v204
	v_mul_f32_e32 v86, 0xbfb8aa3b, v92
	s_waitcnt vmcnt(0)
	v_pk_mul_f32 v[62:63], v[62:63], v[206:207]
	v_mul_f32_e32 v78, 0xbfb8aa3b, v84
	v_exp_f32_e32 v86, v86
	v_exp_f32_e32 v87, v78
	v_pk_mul_f32 v[64:65], v[64:65], v[208:209]
	v_pk_add_f32 v[78:79], v[86:87], 1.0 op_sel_hi:[1,0]
	s_nop 0


; DEV float silu_f(float x) { return x / (1.f + __expf(-x)); }
	s_nop 0


; DEV float silu_f(float x) { return x / (1.f + __expf(-x)); }
	v_rcp_f32_e32 v80, v79
	s_nop 0
	v_mul_f32_e32 v79, v84, v80


; DEV float silu_f(float x) { return x / (1.f + __expf(-x)); }
	s_nop 0


; DEV unsigned cvt_pk_bf16(float lo, float hi) { const f32x2_t v = {lo, hi}; const bf16x2_t b = __builtin_convertvector(v, bf16x2_t); return __builtin_bit_cast(unsigned, b); }
; DEV float bflo(unsigned u) { return __uint_as_float(u << 16); }
; DEV float bfhi(unsigned u) { return __uint_as_float(u & 0xffff0000u); }
; DEV float silu_f(float x) { return x / (1.f + __expf(-x)); }
; template <int WT, class Epi>
; DEV void gemm_tile(const bf16_t* __restrict__ A, int lda, const bf16_t* __restrict__ Bt, int ldb, int K, unsigned char* lds, const Epi& epi) {
;     ...
;                 uint2 w; w.x = cvt_pk_bf16(v[0], v[1]); w.y = cvt_pk_bf16(v[2], v[3]);
;     DEV f32x4 xform(int r, int c, f32x4 v) const {
;     ...
;         o[0] = v[0] * s[0] * silu_f(bflo(z.x)); o[1] = v[1] * s[1] * silu_f(bfhi(z.x));
;         o[2] = v[2] * s[2] * silu_f(bflo(z.y)); o[3] = v[3] * s[3] * silu_f(bfhi(z.y));
	v_rcp_f32_e32 v80, v78
	s_nop 0
	v_mul_f32_e32 v78, v92, v80
	v_lshlrev_b32_e32 v80, 16, v205
	v_and_b32_e32 v81, 0xffff0000, v205
	v_pk_mul_f32 v[62:63], v[62:63], v[78:79]
	v_mul_f32_e32 v78, 0xbfb8aa3b, v80
	v_mul_f32_e32 v79, 0xbfb8aa3b, v81
	v_exp_f32_e32 v78, v78
	v_exp_f32_e32 v79, v79
	v_cvt_pk_bf16_f32 v62, v62, v63
	v_pk_add_f32 v[78:79], v[78:79], 1.0 op_sel_hi:[1,0]
	s_nop 0


; DEV float silu_f(float x) { return x / (1.f + __expf(-x)); }
	s_nop 0


; DEV float silu_f(float x) { return x / (1.f + __expf(-x)); }
	v_rcp_f32_e32 v84, v79
	s_nop 0
	v_mul_f32_e32 v79, v81, v84


; DEV float silu_f(float x) { return x / (1.f + __expf(-x)); }
	s_nop 0


; DEV unsigned cvt_pk_bf16(float lo, float hi) { const f32x2_t v = {lo, hi}; const bf16x2_t b = __builtin_convertvector(v, bf16x2_t); return __builtin_bit_cast(unsigned, b); }
; DEV float bflo(unsigned u) { return __uint_as_float(u << 16); }
; DEV float bfhi(unsigned u) { return __uint_as_float(u & 0xffff0000u); }
; DEV float silu_f(float x) { return x / (1.f + __expf(-x)); }
; template <int WT, class Epi>
; DEV void gemm_tile(const bf16_t* __restrict__ A, int lda, const bf16_t* __restrict__ Bt, int ldb, int K, unsigned char* lds, const Epi& epi) {
;     ...
;                 uint2 w; w.x = cvt_pk_bf16(v[0], v[1]); w.y = cvt_pk_bf16(v[2], v[3]);
;                 *(uint2*)(lds + row * RB + ((((col >> 3) ^ (row & (CPR - 1))) << 4) | (((col >> 2) & 1) << 3))) = w;
;     DEV f32x4 xform(int r, int c, f32x4 v) const {
;     ...
;         o[2] = v[2] * s[2] * silu_f(bflo(z.y)); o[3] = v[3] * s[3] * silu_f(bfhi(z.y));
	v_rcp_f32_e32 v81, v78
	s_nop 0
	v_mul_f32_e32 v78, v80, v81
	v_pk_mul_f32 v[64:65], v[64:65], v[78:79]
	s_nop 0
	v_cvt_pk_bf16_f32 v63, v64, v65
	v_lshrrev_b32_e32 v64, 3, v91
	v_bitop3_b32 v64, v64, v137, 15 bitop3:0x78
	v_lshl_or_b32 v64, v64, 4, v89
	v_add_u32_e32 v65, v90, v64
	ds_write_b64 v65, v[62:63]
	v_or_b32_e32 v65, 48, v88
	v_or_b32_e32 v62, s68, v65
	v_ashrrev_i32_e32 v63, 31, v62
	v_lshlrev_b64 v[62:63], 1, v[62:63]
	v_lshl_add_u64 v[78:79], v[82:83], 0, v[62:63]

; DEV float silu_f(float x) { return x / (1.f + __expf(-x)); }
	s_nop 0

; DEV float bflo(unsigned u) { return __uint_as_float(u << 16); }
; DEV float bfhi(unsigned u) { return __uint_as_float(u & 0xffff0000u); }
; DEV float silu_f(float x) { return x / (1.f + __expf(-x)); }
;     DEV f32x4 xform(int r, int c, f32x4 v) const {
;     ...
;         o[0] = v[0] * s[0] * silu_f(bflo(z.x)); o[1] = v[1] * s[1] * silu_f(bfhi(z.x));
	s_waitcnt vmcnt(1)
	v_lshlrev_b32_e32 v86, 16, v210
	v_and_b32_e32 v82, 0xffff0000, v210
	v_mul_f32_e32 v84, 0xbfb8aa3b, v86
	s_waitcnt vmcnt(0)
	v_pk_mul_f32 v[58:59], v[58:59], v[212:213]
	v_mul_f32_e32 v78, 0xbfb8aa3b, v82
	v_exp_f32_e32 v84, v84
	v_exp_f32_e32 v85, v78
	v_pk_mul_f32 v[60:61], v[60:61], v[214:215]
	v_pk_add_f32 v[78:79], v[84:85], 1.0 op_sel_hi:[1,0]
	s_nop 0


; DEV float silu_f(float x) { return x / (1.f + __expf(-x)); }
	s_nop 0


; DEV float silu_f(float x) { return x / (1.f + __expf(-x)); }
	v_rcp_f32_e32 v80, v79
	s_nop 0
	v_mul_f32_e32 v79, v82, v80


; DEV float silu_f(float x) { return x / (1.f + __expf(-x)); }
	s_nop 0


; DEV float bflo(unsigned u) { return __uint_as_float(u << 16); }
; DEV float bfhi(unsigned u) { return __uint_as_float(u & 0xffff0000u); }
; DEV float silu_f(float x) { return x / (1.f + __expf(-x)); }
;     DEV f32x4 xform(int r, int c, f32x4 v) const {
;     ...
;         o[0] = v[0] * s[0] * silu_f(bflo(z.x)); o[1] = v[1] * s[1] * silu_f(bfhi(z.x));
;         o[2] = v[2] * s[2] * silu_f(bflo(z.y)); o[3] = v[3] * s[3] * silu_f(bfhi(z.y));
	v_rcp_f32_e32 v80, v78
	s_nop 0
	v_mul_f32_e32 v78, v86, v80
	v_lshlrev_b32_e32 v80, 16, v211
	v_and_b32_e32 v81, 0xffff0000, v211
	v_pk_mul_f32 v[58:59], v[58:59], v[78:79]
	v_mul_f32_e32 v78, 0xbfb8aa3b, v80
	v_mul_f32_e32 v79, 0xbfb8aa3b, v81
	v_exp_f32_e32 v78, v78
	v_exp_f32_e32 v79, v79
	s_nop 0
	v_pk_add_f32 v[78:79], v[78:79], 1.0 op_sel_hi:[1,0]
	s_nop 0


; DEV float silu_f(float x) { return x / (1.f + __expf(-x)); }
	s_nop 0


; DEV float silu_f(float x) { return x / (1.f + __expf(-x)); }
	v_rcp_f32_e32 v82, v79
	s_nop 0
	v_mul_f32_e32 v79, v81, v82


; DEV float silu_f(float x) { return x / (1.f + __expf(-x)); }
	s_nop 0


; DEV unsigned cvt_pk_bf16(float lo, float hi) { const f32x2_t v = {lo, hi}; const bf16x2_t b = __builtin_convertvector(v, bf16x2_t); return __builtin_bit_cast(unsigned, b); }
; template <int WT, class Epi>
; DEV void gemm_tile(const bf16_t* __restrict__ A, int lda, const bf16_t* __restrict__ Bt, int ldb, int K, unsigned char* lds, const Epi& epi) {
;     ...
;                 const int row = wr * WT + mi * 16 + fr, col = wc * WT + ni * 16 + fq * 4;
;     ...
;                 uint2 w; w.x = cvt_pk_bf16(v[0], v[1]); w.y = cvt_pk_bf16(v[2], v[3]);
;                 *(uint2*)(lds + row * RB + ((((col >> 3) ^ (row & (CPR - 1))) << 4) | (((col >> 2) & 1) << 3))) = w;
;     DEV f32x4 xform(int r, int c, f32x4 v) const {
;     ...
;         const uint2 z = *(const uint2*)(proj + (size_t)row * NPJ + C_ZB + col);
	v_rcp_f32_e32 v81, v78
	s_nop 0
	v_mul_f32_e32 v78, v80, v81
	v_pk_mul_f32 v[60:61], v[60:61], v[78:79]
	v_cvt_pk_bf16_f32 v78, v58, v59
	v_lshrrev_b32_e32 v58, 3, v65
	v_bitop3_b32 v58, v58, v137, 15 bitop3:0x78
	v_lshl_or_b32 v58, v58, 4, v89
	v_cvt_pk_bf16_f32 v79, v60, v61
	v_add_u32_e32 v59, v90, v58
	ds_write_b64 v59, v[78:79]
	v_or_b32_e32 v59, 16, v130
	v_lshl_add_u32 v65, v59, 8, s70
	v_add_u32_e32 v59, s81, v59
	v_mad_i64_i32 v[60:61], s[68:69], v59, s79, v[172:173]
	v_lshl_add_u64 v[60:61], v[60:61], 0, s[66:67]
	v_lshl_add_u64 v[78:79], v[60:61], 0, v[68:69]

; DEV float bflo(unsigned u) { return __uint_as_float(u << 16); }
; DEV float bfhi(unsigned u) { return __uint_as_float(u & 0xffff0000u); }
; DEV float silu_f(float x) { return x / (1.f + __expf(-x)); }
;     DEV f32x4 xform(int r, int c, f32x4 v) const {
;     ...
;         o[0] = v[0] * s[0] * silu_f(bflo(z.x)); o[1] = v[1] * s[1] * silu_f(bfhi(z.x));
	s_waitcnt vmcnt(0)
	v_lshlrev_b32_e32 v59, 16, v216
	v_and_b32_e32 v78, 0xffff0000, v216
	v_mul_f32_e32 v80, 0xbfb8aa3b, v59
	v_mul_f32_e32 v54, 0xbfb8aa3b, v78
	v_exp_f32_e32 v80, v80
	v_exp_f32_e32 v81, v54
	s_nop 0
	v_pk_add_f32 v[54:55], v[80:81], 1.0 op_sel_hi:[1,0]
	s_nop 0


; DEV float silu_f(float x) { return x / (1.f + __expf(-x)); }
	s_nop 0


; DEV float silu_f(float x) { return x / (1.f + __expf(-x)); }
	v_rcp_f32_e32 v56, v55
	s_nop 0
	v_mul_f32_e32 v55, v78, v56


; DEV float silu_f(float x) { return x / (1.f + __expf(-x)); }
	s_nop 0


; DEV unsigned cvt_pk_bf16(float lo, float hi) { const f32x2_t v = {lo, hi}; const bf16x2_t b = __builtin_convertvector(v, bf16x2_t); return __builtin_bit_cast(unsigned, b); }
; DEV float bflo(unsigned u) { return __uint_as_float(u << 16); }
; DEV float bfhi(unsigned u) { return __uint_as_float(u & 0xffff0000u); }
; DEV float silu_f(float x) { return x / (1.f + __expf(-x)); }
; template <int WT, class Epi>
; DEV void gemm_tile(const bf16_t* __restrict__ A, int lda, const bf16_t* __restrict__ Bt, int ldb, int K, unsigned char* lds, const Epi& epi) {
;     ...
;                 uint2 w; w.x = cvt_pk_bf16(v[0], v[1]); w.y = cvt_pk_bf16(v[2], v[3]);
;     DEV f32x4 xform(int r, int c, f32x4 v) const {
;     ...
;         o[0] = v[0] * s[0] * silu_f(bflo(z.x)); o[1] = v[1] * s[1] * silu_f(bfhi(z.x));
;         o[2] = v[2] * s[2] * silu_f(bflo(z.y)); o[3] = v[3] * s[3] * silu_f(bfhi(z.y));
	v_rcp_f32_e32 v56, v54
	s_nop 0
	v_mul_f32_e32 v54, v59, v56
	v_lshlrev_b32_e32 v56, 16, v217
	v_and_b32_e32 v57, 0xffff0000, v217
	v_pk_mul_f32 v[42:43], v[42:43], v[54:55]
	v_mul_f32_e32 v54, 0xbfb8aa3b, v56
	v_mul_f32_e32 v55, 0xbfb8aa3b, v57
	v_exp_f32_e32 v54, v54
	v_exp_f32_e32 v55, v55
	v_cvt_pk_bf16_f32 v42, v42, v43
	v_pk_add_f32 v[54:55], v[54:55], 1.0 op_sel_hi:[1,0]
	s_nop 0


; DEV float silu_f(float x) { return x / (1.f + __expf(-x)); }
	s_nop 0


; DEV float silu_f(float x) { return x / (1.f + __expf(-x)); }
	v_rcp_f32_e32 v59, v55
	s_nop 0
	v_mul_f32_e32 v55, v57, v59


; DEV float silu_f(float x) { return x / (1.f + __expf(-x)); }
	s_nop 0


; DEV unsigned cvt_pk_bf16(float lo, float hi) { const f32x2_t v = {lo, hi}; const bf16x2_t b = __builtin_convertvector(v, bf16x2_t); return __builtin_bit_cast(unsigned, b); }
; DEV float bflo(unsigned u) { return __uint_as_float(u << 16); }
; DEV float bfhi(unsigned u) { return __uint_as_float(u & 0xffff0000u); }
; DEV float silu_f(float x) { return x / (1.f + __expf(-x)); }
; template <int WT, class Epi>
; DEV void gemm_tile(const bf16_t* __restrict__ A, int lda, const bf16_t* __restrict__ Bt, int ldb, int K, unsigned char* lds, const Epi& epi) {
;     ...
;                 uint2 w; w.x = cvt_pk_bf16(v[0], v[1]); w.y = cvt_pk_bf16(v[2], v[3]);
;                 *(uint2*)(lds + row * RB + ((((col >> 3) ^ (row & (CPR - 1))) << 4) | (((col >> 2) & 1) << 3))) = w;
;     DEV f32x4 xform(int r, int c, f32x4 v) const {
;     ...
;         o[2] = v[2] * s[2] * silu_f(bflo(z.y)); o[3] = v[3] * s[3] * silu_f(bfhi(z.y));
	v_rcp_f32_e32 v57, v54
	s_nop 0
	v_mul_f32_e32 v54, v56, v57
	v_pk_mul_f32 v[44:45], v[44:45], v[54:55]
	s_nop 0
	v_cvt_pk_bf16_f32 v43, v44, v45
	v_add_u32_e32 v44, v65, v76
	ds_write_b64 v44, v[42:43]
	v_lshl_add_u64 v[42:43], v[60:61], 0, v[72:73]

; DEV float bflo(unsigned u) { return __uint_as_float(u << 16); }
; DEV float bfhi(unsigned u) { return __uint_as_float(u & 0xffff0000u); }
; DEV float silu_f(float x) { return x / (1.f + __expf(-x)); }
;     DEV f32x4 xform(int r, int c, f32x4 v) const {
;     ...
;         o[0] = v[0] * s[0] * silu_f(bflo(z.x)); o[1] = v[1] * s[1] * silu_f(bfhi(z.x));
	s_waitcnt vmcnt(0)
	v_lshlrev_b32_e32 v54, 16, v218
	v_and_b32_e32 v42, 0xffff0000, v218
	v_mul_f32_e32 v44, 0xbfb8aa3b, v54
	v_mul_f32_e32 v45, 0xbfb8aa3b, v42
	v_exp_f32_e32 v44, v44
	v_exp_f32_e32 v45, v45
	s_nop 0
	v_pk_add_f32 v[44:45], v[44:45], 1.0 op_sel_hi:[1,0]
	s_nop 0


; DEV float silu_f(float x) { return x / (1.f + __expf(-x)); }
	s_nop 0


; DEV float silu_f(float x) { return x / (1.f + __expf(-x)); }
	v_rcp_f32_e32 v50, v45
	s_nop 0
	v_mul_f32_e32 v45, v42, v50


; DEV float silu_f(float x) { return x / (1.f + __expf(-x)); }
	s_nop 0


; DEV unsigned cvt_pk_bf16(float lo, float hi) { const f32x2_t v = {lo, hi}; const bf16x2_t b = __builtin_convertvector(v, bf16x2_t); return __builtin_bit_cast(unsigned, b); }
; DEV float bflo(unsigned u) { return __uint_as_float(u << 16); }
; DEV float bfhi(unsigned u) { return __uint_as_float(u & 0xffff0000u); }
; DEV float silu_f(float x) { return x / (1.f + __expf(-x)); }
; template <int WT, class Epi>
; DEV void gemm_tile(const bf16_t* __restrict__ A, int lda, const bf16_t* __restrict__ Bt, int ldb, int K, unsigned char* lds, const Epi& epi) {
;     ...
;                 uint2 w; w.x = cvt_pk_bf16(v[0], v[1]); w.y = cvt_pk_bf16(v[2], v[3]);
;     DEV f32x4 xform(int r, int c, f32x4 v) const {
;     ...
;         o[0] = v[0] * s[0] * silu_f(bflo(z.x)); o[1] = v[1] * s[1] * silu_f(bfhi(z.x));
;         o[2] = v[2] * s[2] * silu_f(bflo(z.y)); o[3] = v[3] * s[3] * silu_f(bfhi(z.y));
	v_rcp_f32_e32 v42, v44
	s_nop 0
	v_mul_f32_e32 v44, v54, v42
	v_pk_mul_f32 v[44:45], v[46:47], v[44:45]
	v_lshlrev_b32_e32 v46, 16, v219
	v_and_b32_e32 v47, 0xffff0000, v219
	v_mul_f32_e32 v42, 0xbfb8aa3b, v46
	v_mul_f32_e32 v43, 0xbfb8aa3b, v47
	v_exp_f32_e32 v42, v42
	v_exp_f32_e32 v43, v43
	v_cvt_pk_bf16_f32 v44, v44, v45
	v_pk_add_f32 v[42:43], v[42:43], 1.0 op_sel_hi:[1,0]
	s_nop 0


; DEV float silu_f(float x) { return x / (1.f + __expf(-x)); }
	s_nop 0


; DEV float silu_f(float x) { return x / (1.f + __expf(-x)); }
	v_rcp_f32_e32 v50, v43
	s_nop 0
	v_mul_f32_e32 v43, v47, v50


; DEV float silu_f(float x) { return x / (1.f + __expf(-x)); }
	s_nop 0


; DEV unsigned cvt_pk_bf16(float lo, float hi) { const f32x2_t v = {lo, hi}; const bf16x2_t b = __builtin_convertvector(v, bf16x2_t); return __builtin_bit_cast(unsigned, b); }
; DEV float bflo(unsigned u) { return __uint_as_float(u << 16); }
; DEV float bfhi(unsigned u) { return __uint_as_float(u & 0xffff0000u); }
; DEV float silu_f(float x) { return x / (1.f + __expf(-x)); }
; template <int WT, class Epi>
; DEV void gemm_tile(const bf16_t* __restrict__ A, int lda, const bf16_t* __restrict__ Bt, int ldb, int K, unsigned char* lds, const Epi& epi) {
;     ...
;                 uint2 w; w.x = cvt_pk_bf16(v[0], v[1]); w.y = cvt_pk_bf16(v[2], v[3]);
;                 *(uint2*)(lds + row * RB + ((((col >> 3) ^ (row & (CPR - 1))) << 4) | (((col >> 2) & 1) << 3))) = w;
;     DEV f32x4 xform(int r, int c, f32x4 v) const {
;     ...
;         o[2] = v[2] * s[2] * silu_f(bflo(z.y)); o[3] = v[3] * s[3] * silu_f(bfhi(z.y));
	v_rcp_f32_e32 v47, v42
	s_nop 0
	v_mul_f32_e32 v42, v46, v47
	v_pk_mul_f32 v[42:43], v[48:49], v[42:43]
	s_nop 0
	v_cvt_pk_bf16_f32 v45, v42, v43
	v_add_u32_e32 v42, v65, v77
	ds_write_b64 v42, v[44:45]
	v_lshl_add_u64 v[42:43], v[60:61], 0, v[74:75]

;     DEV f32x4 xform(int r, int c, f32x4 v) const {
;     ...
;         const uint2 z = *(const uint2*)(proj + (size_t)row * NPJ + C_ZB + col);
	s_nop 0

; DEV float bflo(unsigned u) { return __uint_as_float(u << 16); }
; DEV float bfhi(unsigned u) { return __uint_as_float(u & 0xffff0000u); }
; DEV float silu_f(float x) { return x / (1.f + __expf(-x)); }
;     DEV f32x4 xform(int r, int c, f32x4 v) const {
;         const int row = m0 + r, col = n0 + c;
;         const uint2 z = *(const uint2*)(proj + (size_t)row * NPJ + C_ZB + col);
;         const f32x4 s = *(const f32x4*)(scale + col);
;         f32x4 o;
;         o[0] = v[0] * s[0] * silu_f(bflo(z.x)); o[1] = v[1] * s[1] * silu_f(bfhi(z.x));
;         o[2] = v[2] * s[2] * silu_f(bflo(z.y)); o[3] = v[3] * s[3] * silu_f(bfhi(z.y));
	s_waitcnt vmcnt(1)
	v_lshlrev_b32_e32 v50, 16, v220
	v_and_b32_e32 v46, 0xffff0000, v220
	v_mul_f32_e32 v48, 0xbfb8aa3b, v50
	s_waitcnt vmcnt(0)
	v_pk_mul_f32 v[38:39], v[38:39], v[206:207]
	v_mul_f32_e32 v42, 0xbfb8aa3b, v46
	v_exp_f32_e32 v48, v48
	v_exp_f32_e32 v49, v42
	v_pk_mul_f32 v[40:41], v[40:41], v[208:209]
	v_pk_add_f32 v[42:43], v[48:49], 1.0 op_sel_hi:[1,0]
	s_nop 0


; DEV float silu_f(float x) { return x / (1.f + __expf(-x)); }
	s_nop 0


; DEV float silu_f(float x) { return x / (1.f + __expf(-x)); }
	v_rcp_f32_e32 v44, v43
	s_nop 0
	v_mul_f32_e32 v43, v46, v44


; DEV float silu_f(float x) { return x / (1.f + __expf(-x)); }
	s_nop 0


; DEV unsigned cvt_pk_bf16(float lo, float hi) { const f32x2_t v = {lo, hi}; const bf16x2_t b = __builtin_convertvector(v, bf16x2_t); return __builtin_bit_cast(unsigned, b); }
; DEV float bflo(unsigned u) { return __uint_as_float(u << 16); }
; DEV float bfhi(unsigned u) { return __uint_as_float(u & 0xffff0000u); }
; DEV float silu_f(float x) { return x / (1.f + __expf(-x)); }
; template <int WT, class Epi>
; DEV void gemm_tile(const bf16_t* __restrict__ A, int lda, const bf16_t* __restrict__ Bt, int ldb, int K, unsigned char* lds, const Epi& epi) {
;     ...
;                 uint2 w; w.x = cvt_pk_bf16(v[0], v[1]); w.y = cvt_pk_bf16(v[2], v[3]);
;     DEV f32x4 xform(int r, int c, f32x4 v) const {
;     ...
;         o[0] = v[0] * s[0] * silu_f(bflo(z.x)); o[1] = v[1] * s[1] * silu_f(bfhi(z.x));
;         o[2] = v[2] * s[2] * silu_f(bflo(z.y)); o[3] = v[3] * s[3] * silu_f(bfhi(z.y));
	v_rcp_f32_e32 v44, v42
	s_nop 0
	v_mul_f32_e32 v42, v50, v44
	v_lshlrev_b32_e32 v44, 16, v221
	v_and_b32_e32 v45, 0xffff0000, v221
	v_pk_mul_f32 v[38:39], v[38:39], v[42:43]
	v_mul_f32_e32 v42, 0xbfb8aa3b, v44
	v_mul_f32_e32 v43, 0xbfb8aa3b, v45
	v_exp_f32_e32 v42, v42
	v_exp_f32_e32 v43, v43
	v_cvt_pk_bf16_f32 v38, v38, v39
	v_pk_add_f32 v[42:43], v[42:43], 1.0 op_sel_hi:[1,0]
	s_nop 0


; DEV float silu_f(float x) { return x / (1.f + __expf(-x)); }
	s_nop 0


; DEV float silu_f(float x) { return x / (1.f + __expf(-x)); }
	v_rcp_f32_e32 v46, v43
	s_nop 0
	v_mul_f32_e32 v43, v45, v46


; DEV float silu_f(float x) { return x / (1.f + __expf(-x)); }
	s_nop 0


; DEV unsigned cvt_pk_bf16(float lo, float hi) { const f32x2_t v = {lo, hi}; const bf16x2_t b = __builtin_convertvector(v, bf16x2_t); return __builtin_bit_cast(unsigned, b); }
; template <int WT, class Epi>
; DEV void gemm_tile(const bf16_t* __restrict__ A, int lda, const bf16_t* __restrict__ Bt, int ldb, int K, unsigned char* lds, const Epi& epi) {
;     ...
;                 uint2 w; w.x = cvt_pk_bf16(v[0], v[1]); w.y = cvt_pk_bf16(v[2], v[3]);
;                 *(uint2*)(lds + row * RB + ((((col >> 3) ^ (row & (CPR - 1))) << 4) | (((col >> 2) & 1) << 3))) = w;
;     DEV f32x4 xform(int r, int c, f32x4 v) const {
;     ...
;         const uint2 z = *(const uint2*)(proj + (size_t)row * NPJ + C_ZB + col);
	v_rcp_f32_e32 v45, v42
	s_nop 0
	v_mul_f32_e32 v42, v44, v45
	v_pk_mul_f32 v[40:41], v[40:41], v[42:43]
	s_nop 0
	v_cvt_pk_bf16_f32 v39, v40, v41
	v_add_u32_e32 v40, v65, v64
	ds_write_b64 v40, v[38:39]
	v_lshl_add_u64 v[38:39], v[60:61], 0, v[62:63]

;     DEV f32x4 xform(int r, int c, f32x4 v) const {
;     ...
;         const uint2 z = *(const uint2*)(proj + (size_t)row * NPJ + C_ZB + col);
	s_nop 0

; DEV float bflo(unsigned u) { return __uint_as_float(u << 16); }
; DEV float bfhi(unsigned u) { return __uint_as_float(u & 0xffff0000u); }
; DEV float silu_f(float x) { return x / (1.f + __expf(-x)); }
;     DEV f32x4 xform(int r, int c, f32x4 v) const {
;         const int row = m0 + r, col = n0 + c;
;         const uint2 z = *(const uint2*)(proj + (size_t)row * NPJ + C_ZB + col);
;         const f32x4 s = *(const f32x4*)(scale + col);
;         f32x4 o;
;         o[0] = v[0] * s[0] * silu_f(bflo(z.x)); o[1] = v[1] * s[1] * silu_f(bfhi(z.x));
;         o[2] = v[2] * s[2] * silu_f(bflo(z.y)); o[3] = v[3] * s[3] * silu_f(bfhi(z.y));
	s_waitcnt vmcnt(1)
	v_lshlrev_b32_e32 v46, 16, v222
	v_and_b32_e32 v42, 0xffff0000, v222
	v_mul_f32_e32 v44, 0xbfb8aa3b, v46
	s_waitcnt vmcnt(0)
	v_pk_mul_f32 v[34:35], v[34:35], v[212:213]
	v_mul_f32_e32 v38, 0xbfb8aa3b, v42
	v_exp_f32_e32 v44, v44
	v_exp_f32_e32 v45, v38
	v_pk_mul_f32 v[36:37], v[36:37], v[214:215]
	v_pk_add_f32 v[38:39], v[44:45], 1.0 op_sel_hi:[1,0]
	s_nop 0


; DEV float silu_f(float x) { return x / (1.f + __expf(-x)); }
	s_nop 0


; DEV float silu_f(float x) { return x / (1.f + __expf(-x)); }
	v_rcp_f32_e32 v40, v39
	s_nop 0
	v_mul_f32_e32 v39, v42, v40


; DEV float silu_f(float x) { return x / (1.f + __expf(-x)); }
	s_nop 0


; DEV unsigned cvt_pk_bf16(float lo, float hi) { const f32x2_t v = {lo, hi}; const bf16x2_t b = __builtin_convertvector(v, bf16x2_t); return __builtin_bit_cast(unsigned, b); }
; DEV float bflo(unsigned u) { return __uint_as_float(u << 16); }
; DEV float bfhi(unsigned u) { return __uint_as_float(u & 0xffff0000u); }
; DEV float silu_f(float x) { return x / (1.f + __expf(-x)); }
; template <int WT, class Epi>
; DEV void gemm_tile(const bf16_t* __restrict__ A, int lda, const bf16_t* __restrict__ Bt, int ldb, int K, unsigned char* lds, const Epi& epi) {
;     ...
;                 uint2 w; w.x = cvt_pk_bf16(v[0], v[1]); w.y = cvt_pk_bf16(v[2], v[3]);
;     DEV f32x4 xform(int r, int c, f32x4 v) const {
;     ...
;         o[0] = v[0] * s[0] * silu_f(bflo(z.x)); o[1] = v[1] * s[1] * silu_f(bfhi(z.x));
;         o[2] = v[2] * s[2] * silu_f(bflo(z.y)); o[3] = v[3] * s[3] * silu_f(bfhi(z.y));
	v_rcp_f32_e32 v40, v38
	s_nop 0
	v_mul_f32_e32 v38, v46, v40
	v_lshlrev_b32_e32 v40, 16, v223
	v_and_b32_e32 v41, 0xffff0000, v223
	v_pk_mul_f32 v[34:35], v[34:35], v[38:39]
	v_mul_f32_e32 v38, 0xbfb8aa3b, v40
	v_mul_f32_e32 v39, 0xbfb8aa3b, v41
	v_exp_f32_e32 v38, v38
	v_exp_f32_e32 v39, v39
	v_cvt_pk_bf16_f32 v34, v34, v35
	v_pk_add_f32 v[38:39], v[38:39], 1.0 op_sel_hi:[1,0]
	s_nop 0


; DEV float silu_f(float x) { return x / (1.f + __expf(-x)); }
	s_nop 0


; DEV float silu_f(float x) { return x / (1.f + __expf(-x)); }
	v_rcp_f32_e32 v42, v39
	s_nop 0
	v_mul_f32_e32 v39, v41, v42


; DEV float silu_f(float x) { return x / (1.f + __expf(-x)); }
	s_nop 0


; DEV unsigned cvt_pk_bf16(float lo, float hi) { const f32x2_t v = {lo, hi}; const bf16x2_t b = __builtin_convertvector(v, bf16x2_t); return __builtin_bit_cast(unsigned, b); }
; template <int WT, class Epi>
; DEV void gemm_tile(const bf16_t* __restrict__ A, int lda, const bf16_t* __restrict__ Bt, int ldb, int K, unsigned char* lds, const Epi& epi) {
;     ...
;                 const int row = wr * WT + mi * 16 + fr, col = wc * WT + ni * 16 + fq * 4;
;                 const f32x4 v = epi.xform(row, col, acc[mi][ni]);
;                 uint2 w; w.x = cvt_pk_bf16(v[0], v[1]); w.y = cvt_pk_bf16(v[2], v[3]);
;                 *(uint2*)(lds + row * RB + ((((col >> 3) ^ (row & (CPR - 1))) << 4) | (((col >> 2) & 1) << 3))) = w;
;     DEV f32x4 xform(int r, int c, f32x4 v) const {
;     ...
;         const uint2 z = *(const uint2*)(proj + (size_t)row * NPJ + C_ZB + col);
	v_rcp_f32_e32 v41, v38
	s_nop 0
	v_mul_f32_e32 v38, v40, v41
	v_pk_mul_f32 v[36:37], v[36:37], v[38:39]
	s_nop 0
	v_cvt_pk_bf16_f32 v35, v36, v37
	v_add_u32_e32 v36, v65, v58
	ds_write_b64 v36, v[34:35]
	v_or_b32_e32 v34, 32, v130
	v_lshl_add_u32 v44, v34, 8, s70
	v_add_u32_e32 v34, s81, v34
	v_mad_i64_i32 v[34:35], s[68:69], v34, s79, v[172:173]
	v_lshl_add_u64 v[38:39], v[34:35], 0, s[66:67]
	v_lshl_add_u64 v[34:35], v[38:39], 0, v[68:69]

;     DEV f32x4 xform(int r, int c, f32x4 v) const {
;     ...
;         const uint2 z = *(const uint2*)(proj + (size_t)row * NPJ + C_ZB + col);
	s_nop 0

; DEV float bflo(unsigned u) { return __uint_as_float(u << 16); }
; DEV float bfhi(unsigned u) { return __uint_as_float(u & 0xffff0000u); }
; DEV float silu_f(float x) { return x / (1.f + __expf(-x)); }
;     DEV f32x4 xform(int r, int c, f32x4 v) const {
;         const int row = m0 + r, col = n0 + c;
;         const uint2 z = *(const uint2*)(proj + (size_t)row * NPJ + C_ZB + col);
;         const f32x4 s = *(const f32x4*)(scale + col);
;         f32x4 o;
;         o[0] = v[0] * s[0] * silu_f(bflo(z.x)); o[1] = v[1] * s[1] * silu_f(bfhi(z.x));
;         o[2] = v[2] * s[2] * silu_f(bflo(z.y)); o[3] = v[3] * s[3] * silu_f(bfhi(z.y));
	s_waitcnt vmcnt(1)
	v_lshlrev_b32_e32 v45, 16, v224
	v_and_b32_e32 v40, 0xffff0000, v224
	v_mul_f32_e32 v42, 0xbfb8aa3b, v45
	s_waitcnt vmcnt(0)
	v_pk_mul_f32 v[30:31], v[30:31], v[194:195]
	v_mul_f32_e32 v34, 0xbfb8aa3b, v40
	v_exp_f32_e32 v42, v42
	v_exp_f32_e32 v43, v34
	v_pk_mul_f32 v[32:33], v[32:33], v[196:197]
	v_pk_add_f32 v[34:35], v[42:43], 1.0 op_sel_hi:[1,0]
	s_nop 0


; DEV float silu_f(float x) { return x / (1.f + __expf(-x)); }
	s_nop 0


; DEV float silu_f(float x) { return x / (1.f + __expf(-x)); }
	v_rcp_f32_e32 v36, v35
	s_nop 0
	v_mul_f32_e32 v35, v40, v36


; DEV float silu_f(float x) { return x / (1.f + __expf(-x)); }
	s_nop 0


; DEV unsigned cvt_pk_bf16(float lo, float hi) { const f32x2_t v = {lo, hi}; const bf16x2_t b = __builtin_convertvector(v, bf16x2_t); return __builtin_bit_cast(unsigned, b); }
; DEV float bflo(unsigned u) { return __uint_as_float(u << 16); }
; DEV float bfhi(unsigned u) { return __uint_as_float(u & 0xffff0000u); }
; DEV float silu_f(float x) { return x / (1.f + __expf(-x)); }
; template <int WT, class Epi>
; DEV void gemm_tile(const bf16_t* __restrict__ A, int lda, const bf16_t* __restrict__ Bt, int ldb, int K, unsigned char* lds, const Epi& epi) {
;     ...
;                 uint2 w; w.x = cvt_pk_bf16(v[0], v[1]); w.y = cvt_pk_bf16(v[2], v[3]);
;     DEV f32x4 xform(int r, int c, f32x4 v) const {
;     ...
;         o[0] = v[0] * s[0] * silu_f(bflo(z.x)); o[1] = v[1] * s[1] * silu_f(bfhi(z.x));
;         o[2] = v[2] * s[2] * silu_f(bflo(z.y)); o[3] = v[3] * s[3] * silu_f(bfhi(z.y));
	v_rcp_f32_e32 v36, v34
	s_nop 0
	v_mul_f32_e32 v34, v45, v36
	v_lshlrev_b32_e32 v36, 16, v225
	v_and_b32_e32 v37, 0xffff0000, v225
	v_pk_mul_f32 v[30:31], v[30:31], v[34:35]
	v_mul_f32_e32 v34, 0xbfb8aa3b, v36
	v_mul_f32_e32 v35, 0xbfb8aa3b, v37
	v_exp_f32_e32 v34, v34
	v_exp_f32_e32 v35, v35
	v_cvt_pk_bf16_f32 v30, v30, v31
	v_pk_add_f32 v[34:35], v[34:35], 1.0 op_sel_hi:[1,0]
	s_nop 0


; DEV float silu_f(float x) { return x / (1.f + __expf(-x)); }
	s_nop 0


; DEV float silu_f(float x) { return x / (1.f + __expf(-x)); }
	v_rcp_f32_e32 v40, v35
	s_nop 0
	v_mul_f32_e32 v35, v37, v40


; DEV float silu_f(float x) { return x / (1.f + __expf(-x)); }
	s_nop 0


; DEV unsigned cvt_pk_bf16(float lo, float hi) { const f32x2_t v = {lo, hi}; const bf16x2_t b = __builtin_convertvector(v, bf16x2_t); return __builtin_bit_cast(unsigned, b); }
; template <int WT, class Epi>
; DEV void gemm_tile(const bf16_t* __restrict__ A, int lda, const bf16_t* __restrict__ Bt, int ldb, int K, unsigned char* lds, const Epi& epi) {
;     ...
;                 uint2 w; w.x = cvt_pk_bf16(v[0], v[1]); w.y = cvt_pk_bf16(v[2], v[3]);
;                 *(uint2*)(lds + row * RB + ((((col >> 3) ^ (row & (CPR - 1))) << 4) | (((col >> 2) & 1) << 3))) = w;
;     DEV f32x4 xform(int r, int c, f32x4 v) const {
;     ...
;         const uint2 z = *(const uint2*)(proj + (size_t)row * NPJ + C_ZB + col);
	v_rcp_f32_e32 v37, v34
	s_nop 0
	v_mul_f32_e32 v34, v36, v37
	v_pk_mul_f32 v[32:33], v[32:33], v[34:35]
	s_nop 0
	v_cvt_pk_bf16_f32 v31, v32, v33
	v_add_u32_e32 v32, v44, v76
	ds_write_b64 v32, v[30:31]
	v_lshl_add_u64 v[30:31], v[38:39], 0, v[72:73]

;     DEV f32x4 xform(int r, int c, f32x4 v) const {
;     ...
;         const uint2 z = *(const uint2*)(proj + (size_t)row * NPJ + C_ZB + col);
	s_nop 0

; DEV float bflo(unsigned u) { return __uint_as_float(u << 16); }
; DEV float bfhi(unsigned u) { return __uint_as_float(u & 0xffff0000u); }
; DEV float silu_f(float x) { return x / (1.f + __expf(-x)); }
;     DEV f32x4 xform(int r, int c, f32x4 v) const {
;         const int row = m0 + r, col = n0 + c;
;         const uint2 z = *(const uint2*)(proj + (size_t)row * NPJ + C_ZB + col);
;         const f32x4 s = *(const f32x4*)(scale + col);
;         f32x4 o;
;         o[0] = v[0] * s[0] * silu_f(bflo(z.x)); o[1] = v[1] * s[1] * silu_f(bfhi(z.x));
;         o[2] = v[2] * s[2] * silu_f(bflo(z.y)); o[3] = v[3] * s[3] * silu_f(bfhi(z.y));
	s_waitcnt vmcnt(1)
	v_lshlrev_b32_e32 v40, 16, v226
	v_and_b32_e32 v34, 0xffff0000, v226
	v_mul_f32_e32 v36, 0xbfb8aa3b, v40
	s_waitcnt vmcnt(0)
	v_pk_mul_f32 v[26:27], v[26:27], v[200:201]
	v_mul_f32_e32 v30, 0xbfb8aa3b, v34
	v_exp_f32_e32 v36, v36
	v_exp_f32_e32 v37, v30
	v_pk_mul_f32 v[28:29], v[28:29], v[202:203]
	v_pk_add_f32 v[30:31], v[36:37], 1.0 op_sel_hi:[1,0]
	s_nop 0


; DEV float silu_f(float x) { return x / (1.f + __expf(-x)); }
	s_nop 0


; DEV float silu_f(float x) { return x / (1.f + __expf(-x)); }
	v_rcp_f32_e32 v32, v31
	s_nop 0
	v_mul_f32_e32 v31, v34, v32


; DEV float silu_f(float x) { return x / (1.f + __expf(-x)); }
	s_nop 0


; DEV unsigned cvt_pk_bf16(float lo, float hi) { const f32x2_t v = {lo, hi}; const bf16x2_t b = __builtin_convertvector(v, bf16x2_t); return __builtin_bit_cast(unsigned, b); }
; DEV float bflo(unsigned u) { return __uint_as_float(u << 16); }
; DEV float bfhi(unsigned u) { return __uint_as_float(u & 0xffff0000u); }
; DEV float silu_f(float x) { return x / (1.f + __expf(-x)); }
; template <int WT, class Epi>
; DEV void gemm_tile(const bf16_t* __restrict__ A, int lda, const bf16_t* __restrict__ Bt, int ldb, int K, unsigned char* lds, const Epi& epi) {
;     ...
;                 uint2 w; w.x = cvt_pk_bf16(v[0], v[1]); w.y = cvt_pk_bf16(v[2], v[3]);
;     DEV f32x4 xform(int r, int c, f32x4 v) const {
;     ...
;         o[0] = v[0] * s[0] * silu_f(bflo(z.x)); o[1] = v[1] * s[1] * silu_f(bfhi(z.x));
;         o[2] = v[2] * s[2] * silu_f(bflo(z.y)); o[3] = v[3] * s[3] * silu_f(bfhi(z.y));
	v_rcp_f32_e32 v32, v30
	s_nop 0
	v_mul_f32_e32 v30, v40, v32
	v_lshlrev_b32_e32 v32, 16, v227
	v_and_b32_e32 v33, 0xffff0000, v227
	v_pk_mul_f32 v[26:27], v[26:27], v[30:31]
	v_mul_f32_e32 v30, 0xbfb8aa3b, v32
	v_mul_f32_e32 v31, 0xbfb8aa3b, v33
	v_exp_f32_e32 v30, v30
	v_exp_f32_e32 v31, v31
	v_cvt_pk_bf16_f32 v26, v26, v27
	v_pk_add_f32 v[30:31], v[30:31], 1.0 op_sel_hi:[1,0]
	s_nop 0


; DEV float silu_f(float x) { return x / (1.f + __expf(-x)); }
	s_nop 0


; DEV float silu_f(float x) { return x / (1.f + __expf(-x)); }
	v_rcp_f32_e32 v34, v31
	s_nop 0
	v_mul_f32_e32 v31, v33, v34


; DEV float silu_f(float x) { return x / (1.f + __expf(-x)); }
	s_nop 0


; DEV unsigned cvt_pk_bf16(float lo, float hi) { const f32x2_t v = {lo, hi}; const bf16x2_t b = __builtin_convertvector(v, bf16x2_t); return __builtin_bit_cast(unsigned, b); }
; template <int WT, class Epi>
; DEV void gemm_tile(const bf16_t* __restrict__ A, int lda, const bf16_t* __restrict__ Bt, int ldb, int K, unsigned char* lds, const Epi& epi) {
;     ...
;                 uint2 w; w.x = cvt_pk_bf16(v[0], v[1]); w.y = cvt_pk_bf16(v[2], v[3]);
;                 *(uint2*)(lds + row * RB + ((((col >> 3) ^ (row & (CPR - 1))) << 4) | (((col >> 2) & 1) << 3))) = w;
;     DEV f32x4 xform(int r, int c, f32x4 v) const {
;     ...
;         const uint2 z = *(const uint2*)(proj + (size_t)row * NPJ + C_ZB + col);
	v_rcp_f32_e32 v33, v30
	s_nop 0
	v_mul_f32_e32 v30, v32, v33
	v_pk_mul_f32 v[28:29], v[28:29], v[30:31]
	s_nop 0
	v_cvt_pk_bf16_f32 v27, v28, v29
	v_add_u32_e32 v28, v44, v77
	ds_write_b64 v28, v[26:27]
	v_lshl_add_u64 v[26:27], v[38:39], 0, v[74:75]

;     DEV f32x4 xform(int r, int c, f32x4 v) const {
;     ...
;         const uint2 z = *(const uint2*)(proj + (size_t)row * NPJ + C_ZB + col);
	s_nop 0

; DEV float bflo(unsigned u) { return __uint_as_float(u << 16); }
; DEV float bfhi(unsigned u) { return __uint_as_float(u & 0xffff0000u); }
; DEV float silu_f(float x) { return x / (1.f + __expf(-x)); }
;     DEV f32x4 xform(int r, int c, f32x4 v) const {
;         const int row = m0 + r, col = n0 + c;
;         const uint2 z = *(const uint2*)(proj + (size_t)row * NPJ + C_ZB + col);
;         const f32x4 s = *(const f32x4*)(scale + col);
;         f32x4 o;
;         o[0] = v[0] * s[0] * silu_f(bflo(z.x)); o[1] = v[1] * s[1] * silu_f(bfhi(z.x));
;         o[2] = v[2] * s[2] * silu_f(bflo(z.y)); o[3] = v[3] * s[3] * silu_f(bfhi(z.y));
	s_waitcnt vmcnt(1)
	v_lshlrev_b32_e32 v34, 16, v228
	v_and_b32_e32 v30, 0xffff0000, v228
	v_mul_f32_e32 v32, 0xbfb8aa3b, v34
	s_waitcnt vmcnt(0)
	v_pk_mul_f32 v[22:23], v[22:23], v[206:207]
	v_mul_f32_e32 v26, 0xbfb8aa3b, v30
	v_exp_f32_e32 v32, v32
	v_exp_f32_e32 v33, v26
	v_pk_mul_f32 v[24:25], v[24:25], v[208:209]
	v_pk_add_f32 v[26:27], v[32:33], 1.0 op_sel_hi:[1,0]
	s_nop 0


; DEV float silu_f(float x) { return x / (1.f + __expf(-x)); }
	s_nop 0


; DEV float silu_f(float x) { return x / (1.f + __expf(-x)); }
	v_rcp_f32_e32 v28, v27
	s_nop 0
	v_mul_f32_e32 v27, v30, v28


; DEV float silu_f(float x) { return x / (1.f + __expf(-x)); }
	s_nop 0


; DEV unsigned cvt_pk_bf16(float lo, float hi) { const f32x2_t v = {lo, hi}; const bf16x2_t b = __builtin_convertvector(v, bf16x2_t); return __builtin_bit_cast(unsigned, b); }
; DEV float bflo(unsigned u) { return __uint_as_float(u << 16); }
; DEV float bfhi(unsigned u) { return __uint_as_float(u & 0xffff0000u); }
; DEV float silu_f(float x) { return x / (1.f + __expf(-x)); }
; template <int WT, class Epi>
; DEV void gemm_tile(const bf16_t* __restrict__ A, int lda, const bf16_t* __restrict__ Bt, int ldb, int K, unsigned char* lds, const Epi& epi) {
;     ...
;                 uint2 w; w.x = cvt_pk_bf16(v[0], v[1]); w.y = cvt_pk_bf16(v[2], v[3]);
;     DEV f32x4 xform(int r, int c, f32x4 v) const {
;     ...
;         o[0] = v[0] * s[0] * silu_f(bflo(z.x)); o[1] = v[1] * s[1] * silu_f(bfhi(z.x));
;         o[2] = v[2] * s[2] * silu_f(bflo(z.y)); o[3] = v[3] * s[3] * silu_f(bfhi(z.y));
	v_rcp_f32_e32 v28, v26
	s_nop 0
	v_mul_f32_e32 v26, v34, v28
	v_lshlrev_b32_e32 v28, 16, v229
	v_and_b32_e32 v29, 0xffff0000, v229
	v_pk_mul_f32 v[22:23], v[22:23], v[26:27]
	v_mul_f32_e32 v26, 0xbfb8aa3b, v28
	v_mul_f32_e32 v27, 0xbfb8aa3b, v29
	v_exp_f32_e32 v26, v26
	v_exp_f32_e32 v27, v27
	v_cvt_pk_bf16_f32 v22, v22, v23
	v_pk_add_f32 v[26:27], v[26:27], 1.0 op_sel_hi:[1,0]
	s_nop 0


; DEV float silu_f(float x) { return x / (1.f + __expf(-x)); }
	s_nop 0


; DEV float silu_f(float x) { return x / (1.f + __expf(-x)); }
	v_rcp_f32_e32 v30, v27
	s_nop 0
	v_mul_f32_e32 v27, v29, v30


; DEV float silu_f(float x) { return x / (1.f + __expf(-x)); }
	s_nop 0


; DEV unsigned cvt_pk_bf16(float lo, float hi) { const f32x2_t v = {lo, hi}; const bf16x2_t b = __builtin_convertvector(v, bf16x2_t); return __builtin_bit_cast(unsigned, b); }
; template <int WT, class Epi>
; DEV void gemm_tile(const bf16_t* __restrict__ A, int lda, const bf16_t* __restrict__ Bt, int ldb, int K, unsigned char* lds, const Epi& epi) {
;     ...
;                 uint2 w; w.x = cvt_pk_bf16(v[0], v[1]); w.y = cvt_pk_bf16(v[2], v[3]);
;                 *(uint2*)(lds + row * RB + ((((col >> 3) ^ (row & (CPR - 1))) << 4) | (((col >> 2) & 1) << 3))) = w;
;     DEV f32x4 xform(int r, int c, f32x4 v) const {
;     ...
;         const uint2 z = *(const uint2*)(proj + (size_t)row * NPJ + C_ZB + col);
	v_rcp_f32_e32 v29, v26
	s_nop 0
	v_mul_f32_e32 v26, v28, v29
	v_pk_mul_f32 v[24:25], v[24:25], v[26:27]
	s_nop 0
	v_cvt_pk_bf16_f32 v23, v24, v25
	v_add_u32_e32 v24, v44, v64
	ds_write_b64 v24, v[22:23]
	v_lshl_add_u64 v[22:23], v[38:39], 0, v[62:63]

;     DEV f32x4 xform(int r, int c, f32x4 v) const {
;     ...
;         const uint2 z = *(const uint2*)(proj + (size_t)row * NPJ + C_ZB + col);
	s_nop 0

; DEV float bflo(unsigned u) { return __uint_as_float(u << 16); }
; DEV float bfhi(unsigned u) { return __uint_as_float(u & 0xffff0000u); }
; DEV float silu_f(float x) { return x / (1.f + __expf(-x)); }
;     DEV f32x4 xform(int r, int c, f32x4 v) const {
;         const int row = m0 + r, col = n0 + c;
;         const uint2 z = *(const uint2*)(proj + (size_t)row * NPJ + C_ZB + col);
;         const f32x4 s = *(const f32x4*)(scale + col);
;         f32x4 o;
;         o[0] = v[0] * s[0] * silu_f(bflo(z.x)); o[1] = v[1] * s[1] * silu_f(bfhi(z.x));
;         o[2] = v[2] * s[2] * silu_f(bflo(z.y)); o[3] = v[3] * s[3] * silu_f(bfhi(z.y));
	s_waitcnt vmcnt(1)
	v_lshlrev_b32_e32 v30, 16, v230
	v_and_b32_e32 v26, 0xffff0000, v230
	v_mul_f32_e32 v28, 0xbfb8aa3b, v30
	s_waitcnt vmcnt(0)
	v_pk_mul_f32 v[18:19], v[18:19], v[212:213]
	v_mul_f32_e32 v22, 0xbfb8aa3b, v26
	v_exp_f32_e32 v28, v28
	v_exp_f32_e32 v29, v22
	v_pk_mul_f32 v[20:21], v[20:21], v[214:215]
	v_pk_add_f32 v[22:23], v[28:29], 1.0 op_sel_hi:[1,0]
	s_nop 0


; DEV float silu_f(float x) { return x / (1.f + __expf(-x)); }
	s_nop 0


; DEV float silu_f(float x) { return x / (1.f + __expf(-x)); }
	v_rcp_f32_e32 v24, v23
	s_nop 0
	v_mul_f32_e32 v23, v26, v24


; DEV float silu_f(float x) { return x / (1.f + __expf(-x)); }
	s_nop 0


; DEV unsigned cvt_pk_bf16(float lo, float hi) { const f32x2_t v = {lo, hi}; const bf16x2_t b = __builtin_convertvector(v, bf16x2_t); return __builtin_bit_cast(unsigned, b); }
; DEV float bflo(unsigned u) { return __uint_as_float(u << 16); }
; DEV float bfhi(unsigned u) { return __uint_as_float(u & 0xffff0000u); }
; DEV float silu_f(float x) { return x / (1.f + __expf(-x)); }
; template <int WT, class Epi>
; DEV void gemm_tile(const bf16_t* __restrict__ A, int lda, const bf16_t* __restrict__ Bt, int ldb, int K, unsigned char* lds, const Epi& epi) {
;     ...
;                 uint2 w; w.x = cvt_pk_bf16(v[0], v[1]); w.y = cvt_pk_bf16(v[2], v[3]);
;     DEV f32x4 xform(int r, int c, f32x4 v) const {
;     ...
;         o[0] = v[0] * s[0] * silu_f(bflo(z.x)); o[1] = v[1] * s[1] * silu_f(bfhi(z.x));
;         o[2] = v[2] * s[2] * silu_f(bflo(z.y)); o[3] = v[3] * s[3] * silu_f(bfhi(z.y));
	v_rcp_f32_e32 v24, v22
	s_nop 0
	v_mul_f32_e32 v22, v30, v24
	v_lshlrev_b32_e32 v24, 16, v231
	v_and_b32_e32 v25, 0xffff0000, v231
	v_pk_mul_f32 v[18:19], v[18:19], v[22:23]
	v_mul_f32_e32 v22, 0xbfb8aa3b, v24
	v_mul_f32_e32 v23, 0xbfb8aa3b, v25
	v_exp_f32_e32 v22, v22
	v_exp_f32_e32 v23, v23
	v_cvt_pk_bf16_f32 v18, v18, v19
	v_pk_add_f32 v[22:23], v[22:23], 1.0 op_sel_hi:[1,0]
	s_nop 0


; DEV float silu_f(float x) { return x / (1.f + __expf(-x)); }
	s_nop 0


; DEV float silu_f(float x) { return x / (1.f + __expf(-x)); }
	v_rcp_f32_e32 v26, v23
	s_nop 0
	v_mul_f32_e32 v23, v25, v26


; DEV float silu_f(float x) { return x / (1.f + __expf(-x)); }
	s_nop 0


; DEV unsigned cvt_pk_bf16(float lo, float hi) { const f32x2_t v = {lo, hi}; const bf16x2_t b = __builtin_convertvector(v, bf16x2_t); return __builtin_bit_cast(unsigned, b); }
; template <int WT, class Epi>
; DEV void gemm_tile(const bf16_t* __restrict__ A, int lda, const bf16_t* __restrict__ Bt, int ldb, int K, unsigned char* lds, const Epi& epi) {
;     ...
;                 const int row = wr * WT + mi * 16 + fr, col = wc * WT + ni * 16 + fq * 4;
;                 const f32x4 v = epi.xform(row, col, acc[mi][ni]);
;                 uint2 w; w.x = cvt_pk_bf16(v[0], v[1]); w.y = cvt_pk_bf16(v[2], v[3]);
;                 *(uint2*)(lds + row * RB + ((((col >> 3) ^ (row & (CPR - 1))) << 4) | (((col >> 2) & 1) << 3))) = w;
;     DEV f32x4 xform(int r, int c, f32x4 v) const {
;     ...
;         const uint2 z = *(const uint2*)(proj + (size_t)row * NPJ + C_ZB + col);
	v_rcp_f32_e32 v25, v22
	s_nop 0
	v_mul_f32_e32 v22, v24, v25
	v_pk_mul_f32 v[20:21], v[20:21], v[22:23]
	s_nop 0
	v_cvt_pk_bf16_f32 v19, v20, v21
	v_add_u32_e32 v20, v44, v58
	ds_write_b64 v20, v[18:19]
	v_or_b32_e32 v18, 48, v130
	v_lshl_add_u32 v28, v18, 8, s70
	v_add_u32_e32 v18, s81, v18
	v_mad_i64_i32 v[18:19], s[68:69], v18, s79, v[172:173]
	v_lshl_add_u64 v[22:23], v[18:19], 0, s[66:67]
	v_lshl_add_u64 v[18:19], v[22:23], 0, v[68:69]

; DEV float bflo(unsigned u) { return __uint_as_float(u << 16); }
; DEV float bfhi(unsigned u) { return __uint_as_float(u & 0xffff0000u); }
; DEV float silu_f(float x) { return x / (1.f + __expf(-x)); }
;     DEV f32x4 xform(int r, int c, f32x4 v) const {
;         const int row = m0 + r, col = n0 + c;
;         const uint2 z = *(const uint2*)(proj + (size_t)row * NPJ + C_ZB + col);
;         const f32x4 s = *(const f32x4*)(scale + col);
;         f32x4 o;
;         o[0] = v[0] * s[0] * silu_f(bflo(z.x)); o[1] = v[1] * s[1] * silu_f(bfhi(z.x));
;         o[2] = v[2] * s[2] * silu_f(bflo(z.y)); o[3] = v[3] * s[3] * silu_f(bfhi(z.y));
	s_nop 0

; DEV float bflo(unsigned u) { return __uint_as_float(u << 16); }
; DEV float bfhi(unsigned u) { return __uint_as_float(u & 0xffff0000u); }
; DEV float silu_f(float x) { return x / (1.f + __expf(-x)); }
;     DEV f32x4 xform(int r, int c, f32x4 v) const {
;         const int row = m0 + r, col = n0 + c;
;         const uint2 z = *(const uint2*)(proj + (size_t)row * NPJ + C_ZB + col);
;         const f32x4 s = *(const f32x4*)(scale + col);
;         f32x4 o;
;         o[0] = v[0] * s[0] * silu_f(bflo(z.x)); o[1] = v[1] * s[1] * silu_f(bfhi(z.x));
;         o[2] = v[2] * s[2] * silu_f(bflo(z.y)); o[3] = v[3] * s[3] * silu_f(bfhi(z.y));
	s_waitcnt vmcnt(1)
	v_lshlrev_b32_e32 v29, 16, v232
	v_and_b32_e32 v24, 0xffff0000, v232
	v_mul_f32_e32 v26, 0xbfb8aa3b, v29
	s_waitcnt vmcnt(0)
	v_pk_mul_f32 v[14:15], v[14:15], v[194:195]
	v_mul_f32_e32 v18, 0xbfb8aa3b, v24
	v_exp_f32_e32 v26, v26
	v_exp_f32_e32 v27, v18
	v_pk_mul_f32 v[16:17], v[16:17], v[196:197]
	v_pk_add_f32 v[18:19], v[26:27], 1.0 op_sel_hi:[1,0]
	s_nop 0


; DEV float bflo(unsigned u) { return __uint_as_float(u << 16); }
; DEV float bfhi(unsigned u) { return __uint_as_float(u & 0xffff0000u); }
; DEV float silu_f(float x) { return x / (1.f + __expf(-x)); }
;     DEV f32x4 xform(int r, int c, f32x4 v) const {
;     ...
;         const uint2 z = *(const uint2*)(proj + (size_t)row * NPJ + C_ZB + col);
;         const f32x4 s = *(const f32x4*)(scale + col);
;         f32x4 o;
;         o[0] = v[0] * s[0] * silu_f(bflo(z.x)); o[1] = v[1] * s[1] * silu_f(bfhi(z.x));
;         o[2] = v[2] * s[2] * silu_f(bflo(z.y)); o[3] = v[3] * s[3] * silu_f(bfhi(z.y));
	s_nop 0


; DEV float bflo(unsigned u) { return __uint_as_float(u << 16); }
; DEV float bfhi(unsigned u) { return __uint_as_float(u & 0xffff0000u); }
; DEV float silu_f(float x) { return x / (1.f + __expf(-x)); }
;     DEV f32x4 xform(int r, int c, f32x4 v) const {
;     ...
;         o[0] = v[0] * s[0] * silu_f(bflo(z.x)); o[1] = v[1] * s[1] * silu_f(bfhi(z.x));
;         o[2] = v[2] * s[2] * silu_f(bflo(z.y)); o[3] = v[3] * s[3] * silu_f(bfhi(z.y));
	v_rcp_f32_e32 v20, v19
	s_nop 0
	v_mul_f32_e32 v19, v24, v20


; DEV float bflo(unsigned u) { return __uint_as_float(u << 16); }
; DEV float bfhi(unsigned u) { return __uint_as_float(u & 0xffff0000u); }
; DEV float silu_f(float x) { return x / (1.f + __expf(-x)); }
;     DEV f32x4 xform(int r, int c, f32x4 v) const {
;     ...
;         o[0] = v[0] * s[0] * silu_f(bflo(z.x)); o[1] = v[1] * s[1] * silu_f(bfhi(z.x));
;         o[2] = v[2] * s[2] * silu_f(bflo(z.y)); o[3] = v[3] * s[3] * silu_f(bfhi(z.y));
	s_nop 0


; DEV float bflo(unsigned u) { return __uint_as_float(u << 16); }
; DEV float bfhi(unsigned u) { return __uint_as_float(u & 0xffff0000u); }
; DEV float silu_f(float x) { return x / (1.f + __expf(-x)); }
;     DEV f32x4 xform(int r, int c, f32x4 v) const {
;     ...
;         o[0] = v[0] * s[0] * silu_f(bflo(z.x)); o[1] = v[1] * s[1] * silu_f(bfhi(z.x));
;         o[2] = v[2] * s[2] * silu_f(bflo(z.y)); o[3] = v[3] * s[3] * silu_f(bfhi(z.y));
	v_rcp_f32_e32 v20, v18
	s_nop 0
	v_mul_f32_e32 v18, v29, v20
	v_lshlrev_b32_e32 v20, 16, v233
	v_and_b32_e32 v21, 0xffff0000, v233
	v_pk_mul_f32 v[14:15], v[14:15], v[18:19]
	v_mul_f32_e32 v18, 0xbfb8aa3b, v20
	v_mul_f32_e32 v19, 0xbfb8aa3b, v21
	v_exp_f32_e32 v18, v18
	v_exp_f32_e32 v19, v19
	v_cvt_pk_bf16_f32 v14, v14, v15
	v_pk_add_f32 v[18:19], v[18:19], 1.0 op_sel_hi:[1,0]
	s_nop 0


; DEV float bflo(unsigned u) { return __uint_as_float(u << 16); }
; DEV float bfhi(unsigned u) { return __uint_as_float(u & 0xffff0000u); }
; DEV float silu_f(float x) { return x / (1.f + __expf(-x)); }
;     DEV f32x4 xform(int r, int c, f32x4 v) const {
;     ...
;         o[0] = v[0] * s[0] * silu_f(bflo(z.x)); o[1] = v[1] * s[1] * silu_f(bfhi(z.x));
;         o[2] = v[2] * s[2] * silu_f(bflo(z.y)); o[3] = v[3] * s[3] * silu_f(bfhi(z.y));
	s_nop 0


; DEV float bflo(unsigned u) { return __uint_as_float(u << 16); }
; DEV float bfhi(unsigned u) { return __uint_as_float(u & 0xffff0000u); }
; DEV float silu_f(float x) { return x / (1.f + __expf(-x)); }
;     DEV f32x4 xform(int r, int c, f32x4 v) const {
;     ...
;         o[0] = v[0] * s[0] * silu_f(bflo(z.x)); o[1] = v[1] * s[1] * silu_f(bfhi(z.x));
;         o[2] = v[2] * s[2] * silu_f(bflo(z.y)); o[3] = v[3] * s[3] * silu_f(bfhi(z.y));
	v_rcp_f32_e32 v24, v19
	s_nop 0
	v_mul_f32_e32 v19, v21, v24


; DEV float bflo(unsigned u) { return __uint_as_float(u << 16); }
; DEV float bfhi(unsigned u) { return __uint_as_float(u & 0xffff0000u); }
; DEV float silu_f(float x) { return x / (1.f + __expf(-x)); }
;     DEV f32x4 xform(int r, int c, f32x4 v) const {
;     ...
;         o[0] = v[0] * s[0] * silu_f(bflo(z.x)); o[1] = v[1] * s[1] * silu_f(bfhi(z.x));
;         o[2] = v[2] * s[2] * silu_f(bflo(z.y)); o[3] = v[3] * s[3] * silu_f(bfhi(z.y));
	s_nop 0


; DEV unsigned cvt_pk_bf16(float lo, float hi) { const f32x2_t v = {lo, hi}; const bf16x2_t b = __builtin_convertvector(v, bf16x2_t); return __builtin_bit_cast(unsigned, b); }
; DEV float bflo(unsigned u) { return __uint_as_float(u << 16); }
; DEV float bfhi(unsigned u) { return __uint_as_float(u & 0xffff0000u); }
; DEV float silu_f(float x) { return x / (1.f + __expf(-x)); }
; template <int WT, class Epi>
; DEV void gemm_tile(const bf16_t* __restrict__ A, int lda, const bf16_t* __restrict__ Bt, int ldb, int K, unsigned char* lds, const Epi& epi) {
;     ...
;                 const int row = wr * WT + mi * 16 + fr, col = wc * WT + ni * 16 + fq * 4;
;                 const f32x4 v = epi.xform(row, col, acc[mi][ni]);
;                 uint2 w; w.x = cvt_pk_bf16(v[0], v[1]); w.y = cvt_pk_bf16(v[2], v[3]);
;                 *(uint2*)(lds + row * RB + ((((col >> 3) ^ (row & (CPR - 1))) << 4) | (((col >> 2) & 1) << 3))) = w;
;     DEV f32x4 xform(int r, int c, f32x4 v) const {
;     ...
;         o[0] = v[0] * s[0] * silu_f(bflo(z.x)); o[1] = v[1] * s[1] * silu_f(bfhi(z.x));
;         o[2] = v[2] * s[2] * silu_f(bflo(z.y)); o[3] = v[3] * s[3] * silu_f(bfhi(z.y));
	v_rcp_f32_e32 v21, v18
	s_nop 0
	v_mul_f32_e32 v18, v20, v21
	v_pk_mul_f32 v[16:17], v[16:17], v[18:19]
	s_nop 0
	v_cvt_pk_bf16_f32 v15, v16, v17
	v_add_u32_e32 v16, v28, v76
	ds_write_b64 v16, v[14:15]
	v_lshl_add_u64 v[14:15], v[22:23], 0, v[72:73]

; DEV float bflo(unsigned u) { return __uint_as_float(u << 16); }
; DEV float bfhi(unsigned u) { return __uint_as_float(u & 0xffff0000u); }
; DEV float silu_f(float x) { return x / (1.f + __expf(-x)); }
;     DEV f32x4 xform(int r, int c, f32x4 v) const {
;         const int row = m0 + r, col = n0 + c;
;         const uint2 z = *(const uint2*)(proj + (size_t)row * NPJ + C_ZB + col);
;         const f32x4 s = *(const f32x4*)(scale + col);
;         f32x4 o;
;         o[0] = v[0] * s[0] * silu_f(bflo(z.x)); o[1] = v[1] * s[1] * silu_f(bfhi(z.x));
;         o[2] = v[2] * s[2] * silu_f(bflo(z.y)); o[3] = v[3] * s[3] * silu_f(bfhi(z.y));
	s_nop 0

; DEV float bflo(unsigned u) { return __uint_as_float(u << 16); }
; DEV float bfhi(unsigned u) { return __uint_as_float(u & 0xffff0000u); }
; DEV float silu_f(float x) { return x / (1.f + __expf(-x)); }
;     DEV f32x4 xform(int r, int c, f32x4 v) const {
;         const int row = m0 + r, col = n0 + c;
;         const uint2 z = *(const uint2*)(proj + (size_t)row * NPJ + C_ZB + col);
;         const f32x4 s = *(const f32x4*)(scale + col);
;         f32x4 o;
;         o[0] = v[0] * s[0] * silu_f(bflo(z.x)); o[1] = v[1] * s[1] * silu_f(bfhi(z.x));
;         o[2] = v[2] * s[2] * silu_f(bflo(z.y)); o[3] = v[3] * s[3] * silu_f(bfhi(z.y));
	s_waitcnt vmcnt(1)
	v_lshlrev_b32_e32 v24, 16, v234
	v_and_b32_e32 v18, 0xffff0000, v234
	v_mul_f32_e32 v20, 0xbfb8aa3b, v24
	s_waitcnt vmcnt(0)
	v_pk_mul_f32 v[10:11], v[10:11], v[200:201]
	v_mul_f32_e32 v14, 0xbfb8aa3b, v18
	v_exp_f32_e32 v20, v20
	v_exp_f32_e32 v21, v14
	v_pk_mul_f32 v[12:13], v[12:13], v[202:203]
	v_pk_add_f32 v[14:15], v[20:21], 1.0 op_sel_hi:[1,0]
	s_nop 0


; DEV float bflo(unsigned u) { return __uint_as_float(u << 16); }
; DEV float bfhi(unsigned u) { return __uint_as_float(u & 0xffff0000u); }
; DEV float silu_f(float x) { return x / (1.f + __expf(-x)); }
;     DEV f32x4 xform(int r, int c, f32x4 v) const {
;     ...
;         o[0] = v[0] * s[0] * silu_f(bflo(z.x)); o[1] = v[1] * s[1] * silu_f(bfhi(z.x));
;         o[2] = v[2] * s[2] * silu_f(bflo(z.y)); o[3] = v[3] * s[3] * silu_f(bfhi(z.y));
	s_nop 0


; DEV float bflo(unsigned u) { return __uint_as_float(u << 16); }
; DEV float bfhi(unsigned u) { return __uint_as_float(u & 0xffff0000u); }
; DEV float silu_f(float x) { return x / (1.f + __expf(-x)); }
;     DEV f32x4 xform(int r, int c, f32x4 v) const {
;     ...
;         o[0] = v[0] * s[0] * silu_f(bflo(z.x)); o[1] = v[1] * s[1] * silu_f(bfhi(z.x));
;         o[2] = v[2] * s[2] * silu_f(bflo(z.y)); o[3] = v[3] * s[3] * silu_f(bfhi(z.y));
	v_rcp_f32_e32 v16, v15
	s_nop 0
	v_mul_f32_e32 v15, v18, v16


; DEV float bflo(unsigned u) { return __uint_as_float(u << 16); }
; DEV float bfhi(unsigned u) { return __uint_as_float(u & 0xffff0000u); }
; DEV float silu_f(float x) { return x / (1.f + __expf(-x)); }
;     DEV f32x4 xform(int r, int c, f32x4 v) const {
;     ...
;         o[0] = v[0] * s[0] * silu_f(bflo(z.x)); o[1] = v[1] * s[1] * silu_f(bfhi(z.x));
;         o[2] = v[2] * s[2] * silu_f(bflo(z.y)); o[3] = v[3] * s[3] * silu_f(bfhi(z.y));
	s_nop 0


; DEV float bflo(unsigned u) { return __uint_as_float(u << 16); }
; DEV float bfhi(unsigned u) { return __uint_as_float(u & 0xffff0000u); }
; DEV float silu_f(float x) { return x / (1.f + __expf(-x)); }
;     DEV f32x4 xform(int r, int c, f32x4 v) const {
;     ...
;         o[0] = v[0] * s[0] * silu_f(bflo(z.x)); o[1] = v[1] * s[1] * silu_f(bfhi(z.x));
;         o[2] = v[2] * s[2] * silu_f(bflo(z.y)); o[3] = v[3] * s[3] * silu_f(bfhi(z.y));
	v_rcp_f32_e32 v16, v14
	s_nop 0
	v_mul_f32_e32 v14, v24, v16
	v_lshlrev_b32_e32 v16, 16, v235
	v_and_b32_e32 v17, 0xffff0000, v235
	v_pk_mul_f32 v[10:11], v[10:11], v[14:15]
	v_mul_f32_e32 v14, 0xbfb8aa3b, v16
	v_mul_f32_e32 v15, 0xbfb8aa3b, v17
	v_exp_f32_e32 v14, v14
	v_exp_f32_e32 v15, v15
	v_cvt_pk_bf16_f32 v10, v10, v11
	v_pk_add_f32 v[14:15], v[14:15], 1.0 op_sel_hi:[1,0]
	s_nop 0


; DEV float bflo(unsigned u) { return __uint_as_float(u << 16); }
; DEV float bfhi(unsigned u) { return __uint_as_float(u & 0xffff0000u); }
; DEV float silu_f(float x) { return x / (1.f + __expf(-x)); }
;     DEV f32x4 xform(int r, int c, f32x4 v) const {
;     ...
;         o[0] = v[0] * s[0] * silu_f(bflo(z.x)); o[1] = v[1] * s[1] * silu_f(bfhi(z.x));
;         o[2] = v[2] * s[2] * silu_f(bflo(z.y)); o[3] = v[3] * s[3] * silu_f(bfhi(z.y));
	s_nop 0


; DEV float bflo(unsigned u) { return __uint_as_float(u << 16); }
; DEV float bfhi(unsigned u) { return __uint_as_float(u & 0xffff0000u); }
; DEV float silu_f(float x) { return x / (1.f + __expf(-x)); }
;     DEV f32x4 xform(int r, int c, f32x4 v) const {
;     ...
;         o[0] = v[0] * s[0] * silu_f(bflo(z.x)); o[1] = v[1] * s[1] * silu_f(bfhi(z.x));
;         o[2] = v[2] * s[2] * silu_f(bflo(z.y)); o[3] = v[3] * s[3] * silu_f(bfhi(z.y));
	v_rcp_f32_e32 v18, v15
	s_nop 0
	v_mul_f32_e32 v15, v17, v18


; DEV float bflo(unsigned u) { return __uint_as_float(u << 16); }
; DEV float bfhi(unsigned u) { return __uint_as_float(u & 0xffff0000u); }
; DEV float silu_f(float x) { return x / (1.f + __expf(-x)); }
;     DEV f32x4 xform(int r, int c, f32x4 v) const {
;     ...
;         o[0] = v[0] * s[0] * silu_f(bflo(z.x)); o[1] = v[1] * s[1] * silu_f(bfhi(z.x));
;         o[2] = v[2] * s[2] * silu_f(bflo(z.y)); o[3] = v[3] * s[3] * silu_f(bfhi(z.y));
	s_nop 0


; DEV unsigned cvt_pk_bf16(float lo, float hi) { const f32x2_t v = {lo, hi}; const bf16x2_t b = __builtin_convertvector(v, bf16x2_t); return __builtin_bit_cast(unsigned, b); }
; DEV float bflo(unsigned u) { return __uint_as_float(u << 16); }
; DEV float bfhi(unsigned u) { return __uint_as_float(u & 0xffff0000u); }
; DEV float silu_f(float x) { return x / (1.f + __expf(-x)); }
; template <int WT, class Epi>
; DEV void gemm_tile(const bf16_t* __restrict__ A, int lda, const bf16_t* __restrict__ Bt, int ldb, int K, unsigned char* lds, const Epi& epi) {
;     ...
;                 const int row = wr * WT + mi * 16 + fr, col = wc * WT + ni * 16 + fq * 4;
;                 const f32x4 v = epi.xform(row, col, acc[mi][ni]);
;                 uint2 w; w.x = cvt_pk_bf16(v[0], v[1]); w.y = cvt_pk_bf16(v[2], v[3]);
;                 *(uint2*)(lds + row * RB + ((((col >> 3) ^ (row & (CPR - 1))) << 4) | (((col >> 2) & 1) << 3))) = w;
;     DEV f32x4 xform(int r, int c, f32x4 v) const {
;     ...
;         o[0] = v[0] * s[0] * silu_f(bflo(z.x)); o[1] = v[1] * s[1] * silu_f(bfhi(z.x));
;         o[2] = v[2] * s[2] * silu_f(bflo(z.y)); o[3] = v[3] * s[3] * silu_f(bfhi(z.y));
	v_rcp_f32_e32 v17, v14
	s_nop 0
	v_mul_f32_e32 v14, v16, v17
	v_pk_mul_f32 v[12:13], v[12:13], v[14:15]
	s_nop 0
	v_cvt_pk_bf16_f32 v11, v12, v13
	v_add_u32_e32 v12, v28, v77
	ds_write_b64 v12, v[10:11]
	v_lshl_add_u64 v[10:11], v[22:23], 0, v[74:75]

; DEV float bflo(unsigned u) { return __uint_as_float(u << 16); }
; DEV float bfhi(unsigned u) { return __uint_as_float(u & 0xffff0000u); }
; DEV float silu_f(float x) { return x / (1.f + __expf(-x)); }
;     DEV f32x4 xform(int r, int c, f32x4 v) const {
;         const int row = m0 + r, col = n0 + c;
;         const uint2 z = *(const uint2*)(proj + (size_t)row * NPJ + C_ZB + col);
;         const f32x4 s = *(const f32x4*)(scale + col);
;         f32x4 o;
;         o[0] = v[0] * s[0] * silu_f(bflo(z.x)); o[1] = v[1] * s[1] * silu_f(bfhi(z.x));
;         o[2] = v[2] * s[2] * silu_f(bflo(z.y)); o[3] = v[3] * s[3] * silu_f(bfhi(z.y));
	s_nop 0

; DEV float bflo(unsigned u) { return __uint_as_float(u << 16); }
; DEV float bfhi(unsigned u) { return __uint_as_float(u & 0xffff0000u); }
; DEV float silu_f(float x) { return x / (1.f + __expf(-x)); }
;     DEV f32x4 xform(int r, int c, f32x4 v) const {
;         const int row = m0 + r, col = n0 + c;
;         const uint2 z = *(const uint2*)(proj + (size_t)row * NPJ + C_ZB + col);
;         const f32x4 s = *(const f32x4*)(scale + col);
;         f32x4 o;
;         o[0] = v[0] * s[0] * silu_f(bflo(z.x)); o[1] = v[1] * s[1] * silu_f(bfhi(z.x));
;         o[2] = v[2] * s[2] * silu_f(bflo(z.y)); o[3] = v[3] * s[3] * silu_f(bfhi(z.y));
	s_waitcnt vmcnt(1)
	v_lshlrev_b32_e32 v18, 16, v236
	v_and_b32_e32 v14, 0xffff0000, v236
	v_mul_f32_e32 v16, 0xbfb8aa3b, v18
	s_waitcnt vmcnt(0)
	v_pk_mul_f32 v[6:7], v[6:7], v[206:207]
	v_mul_f32_e32 v10, 0xbfb8aa3b, v14
	v_exp_f32_e32 v16, v16
	v_exp_f32_e32 v17, v10
	v_pk_mul_f32 v[8:9], v[8:9], v[208:209]
	v_pk_add_f32 v[10:11], v[16:17], 1.0 op_sel_hi:[1,0]
	s_nop 0


; DEV float bflo(unsigned u) { return __uint_as_float(u << 16); }
; DEV float bfhi(unsigned u) { return __uint_as_float(u & 0xffff0000u); }
; DEV float silu_f(float x) { return x / (1.f + __expf(-x)); }
;     DEV f32x4 xform(int r, int c, f32x4 v) const {
;     ...
;         o[0] = v[0] * s[0] * silu_f(bflo(z.x)); o[1] = v[1] * s[1] * silu_f(bfhi(z.x));
;         o[2] = v[2] * s[2] * silu_f(bflo(z.y)); o[3] = v[3] * s[3] * silu_f(bfhi(z.y));
	s_nop 0


; DEV float bflo(unsigned u) { return __uint_as_float(u << 16); }
; DEV float bfhi(unsigned u) { return __uint_as_float(u & 0xffff0000u); }
; DEV float silu_f(float x) { return x / (1.f + __expf(-x)); }
;     DEV f32x4 xform(int r, int c, f32x4 v) const {
;     ...
;         o[0] = v[0] * s[0] * silu_f(bflo(z.x)); o[1] = v[1] * s[1] * silu_f(bfhi(z.x));
;         o[2] = v[2] * s[2] * silu_f(bflo(z.y)); o[3] = v[3] * s[3] * silu_f(bfhi(z.y));
	v_rcp_f32_e32 v12, v11
	s_nop 0
	v_mul_f32_e32 v11, v14, v12


; DEV float bflo(unsigned u) { return __uint_as_float(u << 16); }
; DEV float bfhi(unsigned u) { return __uint_as_float(u & 0xffff0000u); }
; DEV float silu_f(float x) { return x / (1.f + __expf(-x)); }
;     DEV f32x4 xform(int r, int c, f32x4 v) const {
;     ...
;         o[0] = v[0] * s[0] * silu_f(bflo(z.x)); o[1] = v[1] * s[1] * silu_f(bfhi(z.x));
;         o[2] = v[2] * s[2] * silu_f(bflo(z.y)); o[3] = v[3] * s[3] * silu_f(bfhi(z.y));
	s_nop 0


; DEV float bflo(unsigned u) { return __uint_as_float(u << 16); }
; DEV float bfhi(unsigned u) { return __uint_as_float(u & 0xffff0000u); }
; DEV float silu_f(float x) { return x / (1.f + __expf(-x)); }
;     DEV f32x4 xform(int r, int c, f32x4 v) const {
;     ...
;         o[0] = v[0] * s[0] * silu_f(bflo(z.x)); o[1] = v[1] * s[1] * silu_f(bfhi(z.x));
;         o[2] = v[2] * s[2] * silu_f(bflo(z.y)); o[3] = v[3] * s[3] * silu_f(bfhi(z.y));
	v_rcp_f32_e32 v12, v10
	s_nop 0
	v_mul_f32_e32 v10, v18, v12
	v_lshlrev_b32_e32 v12, 16, v237
	v_and_b32_e32 v13, 0xffff0000, v237
	v_pk_mul_f32 v[6:7], v[6:7], v[10:11]
	v_mul_f32_e32 v10, 0xbfb8aa3b, v12
	v_mul_f32_e32 v11, 0xbfb8aa3b, v13
	v_exp_f32_e32 v10, v10
	v_exp_f32_e32 v11, v11
	v_cvt_pk_bf16_f32 v6, v6, v7
	v_pk_add_f32 v[10:11], v[10:11], 1.0 op_sel_hi:[1,0]
	s_nop 0


; DEV float bflo(unsigned u) { return __uint_as_float(u << 16); }
; DEV float bfhi(unsigned u) { return __uint_as_float(u & 0xffff0000u); }
; DEV float silu_f(float x) { return x / (1.f + __expf(-x)); }
;     DEV f32x4 xform(int r, int c, f32x4 v) const {
;     ...
;         o[0] = v[0] * s[0] * silu_f(bflo(z.x)); o[1] = v[1] * s[1] * silu_f(bfhi(z.x));
;         o[2] = v[2] * s[2] * silu_f(bflo(z.y)); o[3] = v[3] * s[3] * silu_f(bfhi(z.y));
	s_nop 0


; DEV float bflo(unsigned u) { return __uint_as_float(u << 16); }
; DEV float bfhi(unsigned u) { return __uint_as_float(u & 0xffff0000u); }
; DEV float silu_f(float x) { return x / (1.f + __expf(-x)); }
;     DEV f32x4 xform(int r, int c, f32x4 v) const {
;     ...
;         o[0] = v[0] * s[0] * silu_f(bflo(z.x)); o[1] = v[1] * s[1] * silu_f(bfhi(z.x));
;         o[2] = v[2] * s[2] * silu_f(bflo(z.y)); o[3] = v[3] * s[3] * silu_f(bfhi(z.y));
	v_rcp_f32_e32 v14, v11
	s_nop 0
	v_mul_f32_e32 v11, v13, v14


; DEV float bflo(unsigned u) { return __uint_as_float(u << 16); }
; DEV float bfhi(unsigned u) { return __uint_as_float(u & 0xffff0000u); }
; DEV float silu_f(float x) { return x / (1.f + __expf(-x)); }
;     DEV f32x4 xform(int r, int c, f32x4 v) const {
;     ...
;         o[0] = v[0] * s[0] * silu_f(bflo(z.x)); o[1] = v[1] * s[1] * silu_f(bfhi(z.x));
;         o[2] = v[2] * s[2] * silu_f(bflo(z.y)); o[3] = v[3] * s[3] * silu_f(bfhi(z.y));
	s_nop 0


; DEV unsigned cvt_pk_bf16(float lo, float hi) { const f32x2_t v = {lo, hi}; const bf16x2_t b = __builtin_convertvector(v, bf16x2_t); return __builtin_bit_cast(unsigned, b); }
; DEV float bflo(unsigned u) { return __uint_as_float(u << 16); }
; DEV float bfhi(unsigned u) { return __uint_as_float(u & 0xffff0000u); }
; DEV float silu_f(float x) { return x / (1.f + __expf(-x)); }
; template <int WT, class Epi>
; DEV void gemm_tile(const bf16_t* __restrict__ A, int lda, const bf16_t* __restrict__ Bt, int ldb, int K, unsigned char* lds, const Epi& epi) {
;     ...
;                 const int row = wr * WT + mi * 16 + fr, col = wc * WT + ni * 16 + fq * 4;
;                 const f32x4 v = epi.xform(row, col, acc[mi][ni]);
;                 uint2 w; w.x = cvt_pk_bf16(v[0], v[1]); w.y = cvt_pk_bf16(v[2], v[3]);
;                 *(uint2*)(lds + row * RB + ((((col >> 3) ^ (row & (CPR - 1))) << 4) | (((col >> 2) & 1) << 3))) = w;
;     DEV f32x4 xform(int r, int c, f32x4 v) const {
;     ...
;         o[0] = v[0] * s[0] * silu_f(bflo(z.x)); o[1] = v[1] * s[1] * silu_f(bfhi(z.x));
;         o[2] = v[2] * s[2] * silu_f(bflo(z.y)); o[3] = v[3] * s[3] * silu_f(bfhi(z.y));
	v_rcp_f32_e32 v13, v10
	s_nop 0
	v_mul_f32_e32 v10, v12, v13
	v_pk_mul_f32 v[8:9], v[8:9], v[10:11]
	s_nop 0
	v_cvt_pk_bf16_f32 v7, v8, v9
	v_add_u32_e32 v8, v28, v64
	ds_write_b64 v8, v[6:7]
	v_lshl_add_u64 v[6:7], v[22:23], 0, v[62:63]

; DEV float bflo(unsigned u) { return __uint_as_float(u << 16); }
; DEV float bfhi(unsigned u) { return __uint_as_float(u & 0xffff0000u); }
; DEV float silu_f(float x) { return x / (1.f + __expf(-x)); }
;     DEV f32x4 xform(int r, int c, f32x4 v) const {
;         const int row = m0 + r, col = n0 + c;
;         const uint2 z = *(const uint2*)(proj + (size_t)row * NPJ + C_ZB + col);
;         const f32x4 s = *(const f32x4*)(scale + col);
;         f32x4 o;
;         o[0] = v[0] * s[0] * silu_f(bflo(z.x)); o[1] = v[1] * s[1] * silu_f(bfhi(z.x));
;         o[2] = v[2] * s[2] * silu_f(bflo(z.y)); o[3] = v[3] * s[3] * silu_f(bfhi(z.y));
	s_nop 0

; DEV float bflo(unsigned u) { return __uint_as_float(u << 16); }
; DEV float bfhi(unsigned u) { return __uint_as_float(u & 0xffff0000u); }
; DEV float silu_f(float x) { return x / (1.f + __expf(-x)); }
;     DEV f32x4 xform(int r, int c, f32x4 v) const {
;         const int row = m0 + r, col = n0 + c;
;         const uint2 z = *(const uint2*)(proj + (size_t)row * NPJ + C_ZB + col);
;         const f32x4 s = *(const f32x4*)(scale + col);
;         f32x4 o;
;         o[0] = v[0] * s[0] * silu_f(bflo(z.x)); o[1] = v[1] * s[1] * silu_f(bfhi(z.x));
;         o[2] = v[2] * s[2] * silu_f(bflo(z.y)); o[3] = v[3] * s[3] * silu_f(bfhi(z.y));
	s_waitcnt vmcnt(1)
	v_lshlrev_b32_e32 v14, 16, v238
	v_and_b32_e32 v10, 0xffff0000, v238
	v_mul_f32_e32 v12, 0xbfb8aa3b, v14
	s_waitcnt vmcnt(0)
	v_pk_mul_f32 v[2:3], v[2:3], v[212:213]
	v_mul_f32_e32 v6, 0xbfb8aa3b, v10
	v_exp_f32_e32 v12, v12
	v_exp_f32_e32 v13, v6
	v_pk_mul_f32 v[4:5], v[4:5], v[214:215]
	v_pk_add_f32 v[6:7], v[12:13], 1.0 op_sel_hi:[1,0]
	s_nop 0


; DEV float bflo(unsigned u) { return __uint_as_float(u << 16); }
; DEV float bfhi(unsigned u) { return __uint_as_float(u & 0xffff0000u); }
; DEV float silu_f(float x) { return x / (1.f + __expf(-x)); }
;     DEV f32x4 xform(int r, int c, f32x4 v) const {
;     ...
;         o[0] = v[0] * s[0] * silu_f(bflo(z.x)); o[1] = v[1] * s[1] * silu_f(bfhi(z.x));
;         o[2] = v[2] * s[2] * silu_f(bflo(z.y)); o[3] = v[3] * s[3] * silu_f(bfhi(z.y));
	s_nop 0


; DEV float bflo(unsigned u) { return __uint_as_float(u << 16); }
; DEV float bfhi(unsigned u) { return __uint_as_float(u & 0xffff0000u); }
; DEV float silu_f(float x) { return x / (1.f + __expf(-x)); }
;     DEV f32x4 xform(int r, int c, f32x4 v) const {
;     ...
;         o[0] = v[0] * s[0] * silu_f(bflo(z.x)); o[1] = v[1] * s[1] * silu_f(bfhi(z.x));
;         o[2] = v[2] * s[2] * silu_f(bflo(z.y)); o[3] = v[3] * s[3] * silu_f(bfhi(z.y));
	v_rcp_f32_e32 v8, v7
	s_nop 0
	v_mul_f32_e32 v7, v10, v8


; DEV float bflo(unsigned u) { return __uint_as_float(u << 16); }
; DEV float bfhi(unsigned u) { return __uint_as_float(u & 0xffff0000u); }
; DEV float silu_f(float x) { return x / (1.f + __expf(-x)); }
;     DEV f32x4 xform(int r, int c, f32x4 v) const {
;     ...
;         o[0] = v[0] * s[0] * silu_f(bflo(z.x)); o[1] = v[1] * s[1] * silu_f(bfhi(z.x));
;         o[2] = v[2] * s[2] * silu_f(bflo(z.y)); o[3] = v[3] * s[3] * silu_f(bfhi(z.y));
	s_nop 0


; DEV float bflo(unsigned u) { return __uint_as_float(u << 16); }
; DEV float bfhi(unsigned u) { return __uint_as_float(u & 0xffff0000u); }
; DEV float silu_f(float x) { return x / (1.f + __expf(-x)); }
;     DEV f32x4 xform(int r, int c, f32x4 v) const {
;     ...
;         o[0] = v[0] * s[0] * silu_f(bflo(z.x)); o[1] = v[1] * s[1] * silu_f(bfhi(z.x));
;         o[2] = v[2] * s[2] * silu_f(bflo(z.y)); o[3] = v[3] * s[3] * silu_f(bfhi(z.y));
	v_rcp_f32_e32 v8, v6
	s_nop 0
	v_mul_f32_e32 v6, v14, v8
	v_lshlrev_b32_e32 v8, 16, v239
	v_and_b32_e32 v9, 0xffff0000, v239
	v_pk_mul_f32 v[2:3], v[2:3], v[6:7]
	v_mul_f32_e32 v6, 0xbfb8aa3b, v8
	v_mul_f32_e32 v7, 0xbfb8aa3b, v9
	v_exp_f32_e32 v6, v6
	v_exp_f32_e32 v7, v7
	v_cvt_pk_bf16_f32 v2, v2, v3
	v_pk_add_f32 v[6:7], v[6:7], 1.0 op_sel_hi:[1,0]
	s_nop 0


; DEV float bflo(unsigned u) { return __uint_as_float(u << 16); }
; DEV float bfhi(unsigned u) { return __uint_as_float(u & 0xffff0000u); }
; DEV float silu_f(float x) { return x / (1.f + __expf(-x)); }
;     DEV f32x4 xform(int r, int c, f32x4 v) const {
;     ...
;         o[0] = v[0] * s[0] * silu_f(bflo(z.x)); o[1] = v[1] * s[1] * silu_f(bfhi(z.x));
;         o[2] = v[2] * s[2] * silu_f(bflo(z.y)); o[3] = v[3] * s[3] * silu_f(bfhi(z.y));
	s_nop 0


; DEV float bflo(unsigned u) { return __uint_as_float(u << 16); }
; DEV float bfhi(unsigned u) { return __uint_as_float(u & 0xffff0000u); }
; DEV float silu_f(float x) { return x / (1.f + __expf(-x)); }
;     DEV f32x4 xform(int r, int c, f32x4 v) const {
;     ...
;         o[0] = v[0] * s[0] * silu_f(bflo(z.x)); o[1] = v[1] * s[1] * silu_f(bfhi(z.x));
;         o[2] = v[2] * s[2] * silu_f(bflo(z.y)); o[3] = v[3] * s[3] * silu_f(bfhi(z.y));
	v_rcp_f32_e32 v10, v7
	s_nop 0
	v_mul_f32_e32 v7, v9, v10


; DEV float bflo(unsigned u) { return __uint_as_float(u << 16); }
; DEV float bfhi(unsigned u) { return __uint_as_float(u & 0xffff0000u); }
; DEV float silu_f(float x) { return x / (1.f + __expf(-x)); }
;     DEV f32x4 xform(int r, int c, f32x4 v) const {
;     ...
;         o[0] = v[0] * s[0] * silu_f(bflo(z.x)); o[1] = v[1] * s[1] * silu_f(bfhi(z.x));
;         o[2] = v[2] * s[2] * silu_f(bflo(z.y)); o[3] = v[3] * s[3] * silu_f(bfhi(z.y));
	s_nop 0


; template <int WT, class Epi>
; DEV void gemm_tile(const bf16_t* __restrict__ A, int lda, const bf16_t* __restrict__ Bt, int ldb, int K, unsigned char* lds, const Epi& epi) {
;     ...
;         __syncthreads();
; #pragma unroll
;         for (int i = 0; i < (2 * WT * CPR) / 256; ++i) {
;             const int idx = tid + 256 * i, row = idx / CPR, cp = idx % CPR, c = cp ^ (row & (CPR - 1));
;             const uint4 d = *(const uint4*)(lds + row * RB + (cp << 4));
;             *(uint4*)(epi.obase + (size_t)row * epi.old + c * 8) = epi.finish(row, c * 8, d);
;         }
;         __syncthreads();
	v_rcp_f32_e32 v9, v6
	s_nop 0
	v_mul_f32_e32 v6, v8, v9
	v_pk_mul_f32 v[4:5], v[4:5], v[6:7]
	s_nop 0
	v_cvt_pk_bf16_f32 v3, v4, v5
	v_add_u32_e32 v4, v28, v58
	ds_write_b64 v4, v[2:3]
	v_ashrrev_i32_e32 v2, 31, v137
	v_lshrrev_b32_e32 v2, 28, v2
	v_add_u32_e32 v2, v137, v2
	v_ashrrev_i32_e32 v3, 4, v2
	v_and_b32_e32 v2, -16, v2
	v_sub_u32_e32 v2, v137, v2
	v_bitop3_b32 v4, v3, v2, 15 bitop3:0x6c
	v_lshlrev_b32_e32 v5, 8, v3
	v_lshlrev_b32_e32 v2, 4, v2
	v_add3_u32 v8, s70, v5, v2
	v_lshlrev_b32_e32 v2, 3, v4
	v_mad_i64_i32 v[4:5], s[68:69], v3, s80, v[132:133]
	v_ashrrev_i32_e32 v3, 31, v2
	s_waitcnt lgkmcnt(0)
	s_barrier
	v_lshl_add_u64 v[6:7], v[2:3], 1, v[4:5]
	ds_read_b128 v[2:5], v8
	s_waitcnt lgkmcnt(0)
	global_store_dwordx4 v[6:7], v[2:5], off offset:2048
	s_nop 1
	v_add_u32_e32 v2, 0x100, v137
	v_ashrrev_i32_e32 v3, 31, v2
	v_lshrrev_b32_e32 v3, 28, v3
	v_add_u32_e32 v3, v2, v3
	v_ashrrev_i32_e32 v4, 4, v3
	v_and_b32_e32 v3, -16, v3
	v_sub_u32_e32 v2, v2, v3
	v_bitop3_b32 v3, v4, v2, 15 bitop3:0x6c
	v_lshlrev_b32_e32 v5, 8, v4
	v_lshlrev_b32_e32 v2, 4, v2
	v_add3_u32 v8, s70, v5, v2
	v_lshlrev_b32_e32 v2, 3, v3
	v_mad_i64_i32 v[4:5], s[68:69], v4, s80, v[132:133]
	v_ashrrev_i32_e32 v3, 31, v2
	v_lshl_add_u64 v[6:7], v[2:3], 1, v[4:5]
	ds_read_b128 v[2:5], v8
	s_waitcnt lgkmcnt(0)
	global_store_dwordx4 v[6:7], v[2:5], off offset:2048
	s_nop 1
	v_add_u32_e32 v2, 0x200, v137
	v_ashrrev_i32_e32 v3, 31, v2
	v_lshrrev_b32_e32 v3, 28, v3
	v_add_u32_e32 v3, v2, v3
	v_ashrrev_i32_e32 v4, 4, v3
	v_and_b32_e32 v3, -16, v3
	v_sub_u32_e32 v2, v2, v3
	v_bitop3_b32 v3, v4, v2, 15 bitop3:0x6c
	v_lshlrev_b32_e32 v5, 8, v4
	v_lshlrev_b32_e32 v2, 4, v2
	v_add3_u32 v8, s70, v5, v2
	v_lshlrev_b32_e32 v2, 3, v3
	v_mad_i64_i32 v[4:5], s[68:69], v4, s80, v[132:133]
	v_ashrrev_i32_e32 v3, 31, v2
	v_lshl_add_u64 v[6:7], v[2:3], 1, v[4:5]
	ds_read_b128 v[2:5], v8
	s_waitcnt lgkmcnt(0)
	global_store_dwordx4 v[6:7], v[2:5], off offset:2048
	s_nop 1
	v_add_u32_e32 v2, 0x300, v137
	v_ashrrev_i32_e32 v3, 31, v2
	v_lshrrev_b32_e32 v3, 28, v3
	v_add_u32_e32 v3, v2, v3
	v_ashrrev_i32_e32 v4, 4, v3
	v_and_b32_e32 v3, -16, v3
	v_sub_u32_e32 v2, v2, v3
	v_bitop3_b32 v3, v4, v2, 15 bitop3:0x6c
	v_lshlrev_b32_e32 v5, 8, v4
	v_lshlrev_b32_e32 v2, 4, v2
	v_add3_u32 v8, s70, v5, v2
	v_lshlrev_b32_e32 v2, 3, v3
	v_mad_i64_i32 v[4:5], s[68:69], v4, s80, v[132:133]
	v_ashrrev_i32_e32 v3, 31, v2
	v_lshl_add_u64 v[6:7], v[2:3], 1, v[4:5]
	ds_read_b128 v[2:5], v8
	s_waitcnt lgkmcnt(0)
	global_store_dwordx4 v[6:7], v[2:5], off offset:2048
	s_nop 1
	v_add_u32_e32 v2, 0x400, v137
	v_ashrrev_i32_e32 v3, 31, v2
	v_lshrrev_b32_e32 v3, 28, v3
	v_add_u32_e32 v3, v2, v3
	v_ashrrev_i32_e32 v4, 4, v3
	v_and_b32_e32 v3, -16, v3
	v_sub_u32_e32 v2, v2, v3
	v_bitop3_b32 v3, v4, v2, 15 bitop3:0x6c
	v_lshlrev_b32_e32 v5, 8, v4
	v_lshlrev_b32_e32 v2, 4, v2
	v_add3_u32 v8, s70, v5, v2
	v_lshlrev_b32_e32 v2, 3, v3
	v_mad_i64_i32 v[4:5], s[68:69], v4, s80, v[132:133]
	v_ashrrev_i32_e32 v3, 31, v2
	v_lshl_add_u64 v[6:7], v[2:3], 1, v[4:5]
	ds_read_b128 v[2:5], v8
	s_waitcnt lgkmcnt(0)
	global_store_dwordx4 v[6:7], v[2:5], off offset:2048
	s_nop 1
	v_add_u32_e32 v2, 0x500, v137
	v_ashrrev_i32_e32 v3, 31, v2
	v_lshrrev_b32_e32 v3, 28, v3
	v_add_u32_e32 v3, v2, v3
	v_ashrrev_i32_e32 v4, 4, v3
	v_and_b32_e32 v3, -16, v3
	v_sub_u32_e32 v2, v2, v3
	v_bitop3_b32 v3, v4, v2, 15 bitop3:0x6c
	v_lshlrev_b32_e32 v5, 8, v4
	v_lshlrev_b32_e32 v2, 4, v2
	v_add3_u32 v8, s70, v5, v2
	v_lshlrev_b32_e32 v2, 3, v3
	v_mad_i64_i32 v[4:5], s[68:69], v4, s80, v[132:133]
	v_ashrrev_i32_e32 v3, 31, v2
	v_lshl_add_u64 v[6:7], v[2:3], 1, v[4:5]
	ds_read_b128 v[2:5], v8
	s_waitcnt lgkmcnt(0)
	global_store_dwordx4 v[6:7], v[2:5], off offset:2048
	s_nop 1
	v_add_u32_e32 v2, 0x600, v137
	v_ashrrev_i32_e32 v3, 31, v2
	v_lshrrev_b32_e32 v3, 28, v3
	v_add_u32_e32 v3, v2, v3
	v_ashrrev_i32_e32 v4, 4, v3
	v_and_b32_e32 v3, -16, v3
	v_sub_u32_e32 v2, v2, v3
	v_bitop3_b32 v3, v4, v2, 15 bitop3:0x6c
	v_lshlrev_b32_e32 v5, 8, v4
	v_lshlrev_b32_e32 v2, 4, v2
	v_add3_u32 v8, s70, v5, v2
	v_lshlrev_b32_e32 v2, 3, v3
	v_mad_i64_i32 v[4:5], s[68:69], v4, s80, v[132:133]
	v_ashrrev_i32_e32 v3, 31, v2
	v_lshl_add_u64 v[6:7], v[2:3], 1, v[4:5]
	ds_read_b128 v[2:5], v8
	s_waitcnt lgkmcnt(0)
	global_store_dwordx4 v[6:7], v[2:5], off offset:2048
	s_nop 1
	v_add_u32_e32 v2, 0x700, v137
	v_ashrrev_i32_e32 v3, 31, v2
	v_lshrrev_b32_e32 v3, 28, v3
	v_add_u32_e32 v3, v2, v3
	v_ashrrev_i32_e32 v4, 4, v3
	v_and_b32_e32 v3, -16, v3
	v_sub_u32_e32 v2, v2, v3
	v_bitop3_b32 v3, v4, v2, 15 bitop3:0x6c
	v_lshlrev_b32_e32 v5, 8, v4
	v_lshlrev_b32_e32 v2, 4, v2
	v_add3_u32 v8, s70, v5, v2
	v_lshlrev_b32_e32 v2, 3, v3
	v_mad_i64_i32 v[4:5], s[68:69], v4, s80, v[132:133]
	v_ashrrev_i32_e32 v3, 31, v2
	v_lshl_add_u64 v[6:7], v[2:3], 1, v[4:5]
	ds_read_b128 v[2:5], v8
	s_waitcnt lgkmcnt(0)
	global_store_dwordx4 v[6:7], v[2:5], off offset:2048
	s_barrier
	s_cbranch_scc1 .LBB0_870

; DEV void xcd_barrier(const XcdBarrier& b) {
;     asm volatile("s_waitcnt vmcnt(0)" ::: "memory");
;     __syncthreads();
;     if (threadIdx.x == 0) {
;         unsigned* bar = b.bar;
;         __builtin_amdgcn_s_waitcnt(0);
;         unsigned nloc = b.st[0], nx = b.st[1];
;         if (nloc == 0u) { xcd_barrier_complete(bar, b.x, nloc, nx); b.st[0] = nloc; b.st[1] = nx; }
; __global__ void __launch_bounds__(512) hymba_fwd(Params p) {
;     ...
;         const int nsb = G >> 1;
;         if (bid < nsb) {
;             if (G == 256) {
;                 const int x = bid & 7, j = bid >> 3;
;                 gdn_scan_item(p, ((x * 4 + (j >> 2)) << 3) | ((j & 3) << 1) | vb, vlds);
;             } else
;             for (int t0 = 2 * bid; t0 < NSC; t0 += 2 * nsb) gdn_scan_item(p, min(t0 + vb, NSC - 1), vlds);
;         } else {
;             const int ob = bid - nsb, no = G - nsb;
;             for (int t0 = 2 * ob; t0 < NSM; t0 += 2 * no) gdn_sample_item(p, min(t0 + vb, NSM - 1), vlds);
;             for (int t0 = 2 * ob; t0 < NPL; t0 += 2 * no) { const int t = min(t0 + vb, NPL - 1); int nt, mt; tile_map(t, 68, 8, mt, nt); const int g = nt >> 1;
;                 EpiPoolS e{mt * 128, nt * 128, proj, p.in[15], mix + (size_t)mt * 128 * LDB + 1024 + nt * 128, LDB};
;                 gemm_tile<64>(dpl + (size_t)mt * 128 * LDP + g * 256, LDP, Wt_pool + (size_t)nt * 128 * LDM, LDM, 256, vlds, e);
.Lscan_stag1:
	s_barrier
	s_cmpk_lg_i32 s33, 0x100
	s_cbranch_scc1 .Lpool_scan_skip
	s_cmpk_gt_u32 s2, 15
	s_cbranch_scc1 .Lpool_scan_skip
	s_movk_i32 s31, 0x80
	s_add_i32 s35, s2, 0x100
	s_lshl_b32 s72, s35, 1
	s_movk_i32 s98, 0x220
	s_mov_b64 s[4:5], 0x4288000
	v_lshl_add_u64 v[138:139], v[158:159], 0, s[4:5]
	s_mov_b64 s[4:5], 0x15309000
	v_lshl_add_u64 v[140:141], v[158:159], 0, s[4:5]
	s_branch .Lpool_in
.Lpool_scan_skip:
.LBB0_890:
	s_waitcnt vmcnt(0)
	s_barrier
	s_and_saveexec_b64 s[4:5], s[94:95]
	s_cbranch_execz .LBB0_942
	v_mov_b32_e32 v1, 0x20000
	s_waitcnt vmcnt(0) expcnt(0) lgkmcnt(0)
	ds_read_b32 v3, v1
	v_mov_b32_e32 v1, 0x20004
	ds_read_b32 v1, v1
	s_waitcnt lgkmcnt(1)
	v_cmp_ne_u32_e32 vcc, 0, v3
	s_cbranch_vccnz .LBB0_906
	s_add_u32 s6, s28, 0x1000
	s_addc_u32 s7, s29, 0
	s_add_u32 s8, s28, 0x1100
	s_addc_u32 s9, s29, 0
	s_add_u32 s10, s28, 0x1200
	s_addc_u32 s11, s29, 0
	s_add_u32 s12, s28, 0x1300
	s_addc_u32 s13, s29, 0
	s_mov_b32 s22, 1
	v_mov_b32_e32 v17, 0
	s_branch .LBB0_894
